# SSD3 conv staging: 14 of the 16 row loads issued together with the history rows before the first wait (was three serialized round trips per unit), counted vmcnt ladder re-derived; A_log load in the dt
# speedup vs baseline: 1.0094x; 1.0094x over previous
; template <bool WITH_C, bool B_TR>
; __device__ __forceinline__ void ssd_stage(const Params& p, LAS unsigned char* lds, int b, int c, int g) {
;     ...
;         const int tb = 64 * c + 16 * seg;
;         const bf16_t* src = (const bf16_t*)(p.ws + WS_XBC) + ((size_t)b * SEQ + tb) * D_XBC + col0;
;         const u32x4 zz = {0u, 0u, 0u, 0u};
;         u32x4 rows[19];
;         rows[0] = tb >= 3 ? *(const u32x4*)(src - 3 * D_XBC) : zz; rows[1] = tb >= 2 ? *(const u32x4*)(src - 2 * D_XBC) : zz; rows[2] = tb >= 1 ? *(const u32x4*)(src - 1 * D_XBC) : zz;
; #pragma unroll
;         for (int tt = 0; tt < 16; ++tt) rows[3 + tt] = *(const u32x4*)(src + (size_t)tt * D_XBC);
;         float u1[8], u2[8], u3[8];
;         unpack8(rows[0], u3); unpack8(rows[1], u2); unpack8(rows[2], u1);
; #pragma unroll
;         for (int hb = 0; hb < 2; ++hb) {
;             float y[8][8];
; #pragma unroll
;             for (int tt = 0; tt < 8; ++tt) {
;                 float u0[8]; unpack8(rows[3 + 8 * hb + tt], u0);
; #pragma unroll
;                 for (int i = 0; i < 8; ++i) { const float a = w0[i] * u3[i] + w1[i] * u2[i] + w2[i] * u1[i] + w3[i] * u0[i] + bs[i]; y[tt][i] = a * __builtin_amdgcn_rcpf(1.f + __expf(-a)); u3[i] = u2[i]; u2[i] = u1[i]; u1[i] = u0[i]; }
.LBB0_863:
	s_or_b64 exec, exec, s[62:63]
	s_mov_b32 s101, 0
	global_load_dwordx4 v[136:139], v[40:41], off
	s_movk_i32 s100, 0x1000
	v_lshl_add_u64 v[42:43], v[40:41], 0, s[100:101]
	global_load_dwordx4 v[96:99], v[42:43], off offset:2048
	s_movk_i32 s100, 0x3000
	v_lshl_add_u64 v[42:43], v[40:41], 0, s[100:101]
	global_load_dwordx4 v[92:95], v[42:43], off
	s_movk_i32 s100, 0x4000
	v_lshl_add_u64 v[42:43], v[40:41], 0, s[100:101]
	global_load_dwordx4 v[88:91], v[42:43], off offset:2048
	s_movk_i32 s100, 0x6000
	v_lshl_add_u64 v[42:43], v[40:41], 0, s[100:101]
	global_load_dwordx4 v[84:87], v[42:43], off
	s_movk_i32 s100, 0x7000
	v_lshl_add_u64 v[42:43], v[40:41], 0, s[100:101]
	global_load_dwordx4 v[80:83], v[42:43], off offset:2048
	s_mov_b32 s100, 0x9000
	v_lshl_add_u64 v[42:43], v[40:41], 0, s[100:101]
	global_load_dwordx4 v[76:79], v[42:43], off
	s_mov_b32 s100, 0xa000
	v_lshl_add_u64 v[42:43], v[40:41], 0, s[100:101]
	global_load_dwordx4 v[72:75], v[42:43], off offset:2048
	s_mov_b32 s100, 0xc000
	v_lshl_add_u64 v[42:43], v[40:41], 0, s[100:101]
	global_load_dwordx4 v[68:71], v[42:43], off
	s_mov_b32 s100, 0xd000
	v_lshl_add_u64 v[42:43], v[40:41], 0, s[100:101]
	global_load_dwordx4 v[64:67], v[42:43], off offset:2048
	s_mov_b32 s100, 0xf000
	v_lshl_add_u64 v[42:43], v[40:41], 0, s[100:101]
	global_load_dwordx4 v[60:63], v[42:43], off
	s_mov_b32 s100, 0x10000
	v_lshl_add_u64 v[42:43], v[40:41], 0, s[100:101]
	global_load_dwordx4 v[56:59], v[42:43], off offset:2048
	s_mov_b32 s100, 0x12000
	v_lshl_add_u64 v[42:43], v[40:41], 0, s[100:101]
	global_load_dwordx4 v[52:55], v[42:43], off
	s_mov_b32 s100, 0x13000
	v_lshl_add_u64 v[42:43], v[40:41], 0, s[100:101]
	global_load_dwordx4 v[48:51], v[42:43], off offset:2048
	s_movk_i32 s44, 0x1000
	v_add_co_u32_e32 v42, vcc, s44, v40
	s_waitcnt vmcnt(14)
	v_lshlrev_b32_e32 v144, 16, v100
	v_addc_co_u32_e32 v43, vcc, 0, v41, vcc
	s_nop 0
	s_nop 0
	v_and_b32_e32 v145, 0xffff0000, v100
	v_lshlrev_b32_e32 v146, 16, v101
	v_and_b32_e32 v147, 0xffff0000, v101
	v_mov_b32_e32 v100, 0x16800
	v_mov_b32_e32 v101, 0x12000
	v_cndmask_b32_e64 v100, v100, v101, s[42:43]
	v_cndmask_b32_e64 v101, v209, v210, s[42:43]
	v_lshlrev_b32_e32 v135, 16, v104
	v_add_u32_e32 v134, v101, v133
	v_mul_f32_e32 v101, v24, v144
	v_lshlrev_b32_e32 v140, 16, v105
	v_lshlrev_b32_e32 v141, 16, v106
	v_and_b32_e32 v142, 0xffff0000, v106
	v_lshlrev_b32_e32 v152, 16, v108
	v_fmac_f32_e32 v101, v20, v135
	v_mul_f32_e32 v106, v26, v146
	s_movk_i32 s44, 0x3000
	v_lshlrev_b32_e32 v154, 16, v109
	v_fmac_f32_e32 v101, v28, v152
	v_fmac_f32_e32 v106, v22, v140
	v_add_co_u32_e32 v42, vcc, s44, v40
	v_fmac_f32_e32 v106, v30, v154
	s_nop 0
	v_addc_co_u32_e32 v43, vcc, 0, v41, vcc
	s_movk_i32 s44, 0x4000
	v_add_co_u32_e32 v44, vcc, s44, v40
	v_and_b32_e32 v104, 0xffff0000, v104
	v_lshlrev_b32_e32 v148, 16, v102
	v_and_b32_e32 v149, 0xffff0000, v102
	v_lshlrev_b32_e32 v150, 16, v103
	v_and_b32_e32 v151, 0xffff0000, v103
	v_and_b32_e32 v155, 0xffff0000, v109
	v_mul_f32_e32 v103, v25, v145
	v_addc_co_u32_e32 v45, vcc, 0, v41, vcc
	s_nop 0
	s_nop 0
	v_and_b32_e32 v153, 0xffff0000, v108
	v_fmac_f32_e32 v103, v21, v104
	v_fmac_f32_e32 v103, v29, v153
	v_and_b32_e32 v105, 0xffff0000, v105
	v_lshlrev_b32_e32 v156, 16, v110
	v_and_b32_e32 v157, 0xffff0000, v110
	v_lshlrev_b32_e32 v158, 16, v111
	v_and_b32_e32 v159, 0xffff0000, v111
	v_lshlrev_b32_e32 v143, 16, v107
	v_and_b32_e32 v107, 0xffff0000, v107
	v_mul_f32_e32 v133, v7, v151
	v_fmac_f32_e32 v133, v3, v107
	v_fmac_f32_e32 v133, v11, v159
	s_movk_i32 s44, 0x6000
	v_add_co_u32_e32 v42, vcc, s44, v40
	s_movk_i32 s44, 0x7000
	s_nop 0
	v_addc_co_u32_e32 v43, vcc, 0, v41, vcc
	v_add_co_u32_e32 v44, vcc, s44, v40
	s_mov_b32 s44, 0x9000
	s_nop 0
	v_addc_co_u32_e32 v45, vcc, 0, v41, vcc
	s_nop 0
	s_nop 0
	v_add_co_u32_e32 v42, vcc, s44, v40
	s_mov_b32 s44, 0xa000
	s_nop 0
	v_addc_co_u32_e32 v43, vcc, 0, v41, vcc
	v_add_co_u32_e32 v44, vcc, s44, v40
	s_mov_b32 s44, 0xc000
	s_nop 0
	v_addc_co_u32_e32 v45, vcc, 0, v41, vcc
	s_nop 0
	s_nop 0
	v_add_co_u32_e32 v42, vcc, s44, v40
	s_mov_b32 s44, 0xd000
	s_nop 0
	v_addc_co_u32_e32 v43, vcc, 0, v41, vcc
	s_waitcnt vmcnt(13)
	v_lshlrev_b32_e32 v160, 16, v136
	v_lshlrev_b32_e32 v195, 16, v137
	v_fmac_f32_e32 v101, v32, v160
	v_add_f32_e32 v101, v36, v101
	v_fmac_f32_e32 v106, v34, v195
	v_mul_f32_e32 v102, 0xbfb8aa3b, v101
	v_add_f32_e32 v109, v38, v106
	v_exp_f32_e32 v102, v102
	v_mul_f32_e32 v106, 0xbfb8aa3b, v109
	v_and_b32_e32 v161, 0xffff0000, v136
	v_exp_f32_e32 v106, v106
	v_fmac_f32_e32 v103, v33, v161
	v_add_f32_e32 v103, v37, v103
	v_add_f32_e32 v102, 1.0, v102
	v_mul_f32_e32 v104, 0xbfb8aa3b, v103
	v_exp_f32_e32 v104, v104
	v_rcp_f32_e32 v102, v102
	v_add_f32_e32 v106, 1.0, v106
	v_rcp_f32_e32 v110, v106
	v_mul_f32_e32 v106, v27, v147
	v_fmac_f32_e32 v106, v23, v105
	v_and_b32_e32 v206, 0xffff0000, v137
	v_fmac_f32_e32 v106, v31, v155
	v_add_f32_e32 v104, 1.0, v104
	v_fmac_f32_e32 v106, v35, v206
	v_mul_f32_e32 v108, v101, v102
	v_mul_f32_e32 v102, v4, v148
	v_rcp_f32_e32 v104, v104
	v_add_f32_e32 v105, v39, v106
	v_fmac_f32_e32 v102, v0, v141
	v_lshlrev_b32_e32 v227, 16, v138
	v_mul_f32_e32 v106, 0xbfb8aa3b, v105
	v_fmac_f32_e32 v102, v8, v156
	v_exp_f32_e32 v111, v106
	v_fmac_f32_e32 v102, v12, v227
	v_add_f32_e32 v102, v16, v102
	v_mul_f32_e32 v106, v103, v104
	v_mul_f32_e32 v104, 0xbfb8aa3b, v102
	v_mul_f32_e32 v103, v109, v110
	v_exp_f32_e32 v109, v104
	v_mul_f32_e32 v104, v5, v149
	v_add_f32_e32 v101, 1.0, v111
	v_fmac_f32_e32 v104, v1, v142
	v_and_b32_e32 v228, 0xffff0000, v138
	v_rcp_f32_e32 v101, v101
	v_fmac_f32_e32 v104, v9, v157
	v_fmac_f32_e32 v104, v13, v228
	v_add_f32_e32 v110, v17, v104
	v_mul_f32_e32 v104, 0xbfb8aa3b, v110
	v_exp_f32_e32 v111, v104
	v_mul_f32_e32 v104, v105, v101
	v_add_f32_e32 v101, 1.0, v109
	v_mul_f32_e32 v109, v6, v150
	v_fmac_f32_e32 v109, v2, v143
	v_lshlrev_b32_e32 v229, 16, v139
	v_fmac_f32_e32 v109, v10, v158
	v_fmac_f32_e32 v109, v14, v229
	v_add_f32_e32 v109, v18, v109
	v_add_f32_e32 v105, 1.0, v111
	v_mul_f32_e32 v111, 0xbfb8aa3b, v109
	v_and_b32_e32 v139, 0xffff0000, v139
	v_exp_f32_e32 v111, v111
	v_fmac_f32_e32 v133, v15, v139
	v_add_f32_e32 v133, v19, v133
	v_mul_f32_e32 v107, 0xbfb8aa3b, v133
	v_exp_f32_e32 v107, v107
	v_add_f32_e32 v111, 1.0, v111
	v_rcp_f32_e32 v101, v101
	v_rcp_f32_e32 v111, v111
	s_waitcnt vmcnt(12)
; template <bool WITH_C, bool B_TR>
; __device__ __forceinline__ void ssd_stage(const Params& p, LAS unsigned char* lds, int b, int c, int g) {
;     ...
;         for (int tt = 0; tt < 16; ++tt) rows[3 + tt] = *(const u32x4*)(src + (size_t)tt * D_XBC);
;         float u1[8], u2[8], u3[8];
;         unpack8(rows[0], u3); unpack8(rows[1], u2); unpack8(rows[2], u1);
; #pragma unroll
;         for (int hb = 0; hb < 2; ++hb) {
;             float y[8][8];
; #pragma unroll
;             for (int tt = 0; tt < 8; ++tt) {
;                 float u0[8]; unpack8(rows[3 + 8 * hb + tt], u0);
; #pragma unroll
;                 for (int i = 0; i < 8; ++i) { const float a = w0[i] * u3[i] + w1[i] * u2[i] + w2[i] * u1[i] + w3[i] * u0[i] + bs[i]; y[tt][i] = a * __builtin_amdgcn_rcpf(1.f + __expf(-a)); u3[i] = u2[i]; u2[i] = u1[i]; u1[i] = u0[i]; }
	v_lshlrev_b32_e32 v140, 16, v96
	v_and_b32_e32 v141, 0xffff0000, v96
	v_mul_f32_e32 v96, v24, v152
	v_fmac_f32_e32 v96, v20, v144
	v_add_f32_e32 v107, 1.0, v107
	v_fmac_f32_e32 v96, v28, v160
	v_rcp_f32_e32 v135, v107
	v_mul_f32_e32 v107, v102, v101
	v_mul_f32_e32 v102, v109, v111
	v_fmac_f32_e32 v96, v32, v140
	v_mul_f32_e32 v109, v26, v154
	v_rcp_f32_e32 v105, v105
	v_add_f32_e32 v96, v36, v96
	v_fmac_f32_e32 v109, v22, v146
	v_lshlrev_b32_e32 v142, 16, v97
	v_and_b32_e32 v143, 0xffff0000, v97
	v_lshlrev_b32_e32 v231, 16, v98
	v_mul_f32_e32 v97, 0xbfb8aa3b, v96
	v_and_b32_e32 v144, 0xffff0000, v98
	v_mul_f32_e32 v98, v25, v153
	v_fmac_f32_e32 v109, v30, v195
	v_exp_f32_e32 v97, v97
	v_fmac_f32_e32 v98, v21, v145
	v_fmac_f32_e32 v109, v34, v142
	v_fmac_f32_e32 v98, v29, v161
	v_add_f32_e32 v109, v38, v109
	v_mul_f32_e32 v105, v110, v105
	v_fmac_f32_e32 v98, v33, v141
	v_mul_f32_e32 v110, 0xbfb8aa3b, v109
	v_add_f32_e32 v98, v37, v98
	v_exp_f32_e32 v110, v110
	v_lshlrev_b32_e32 v232, 16, v99
	v_and_b32_e32 v233, 0xffff0000, v99
	v_add_f32_e32 v97, 1.0, v97
	v_mul_f32_e32 v99, 0xbfb8aa3b, v98
	v_exp_f32_e32 v99, v99
	v_rcp_f32_e32 v97, v97
	v_add_f32_e32 v110, 1.0, v110
	v_rcp_f32_e32 v111, v110
	v_mul_f32_e32 v110, v27, v155
	v_mul_f32_e32 v101, v133, v135
	v_add_f32_e32 v99, 1.0, v99
	v_fmac_f32_e32 v110, v23, v147
	v_mul_f32_e32 v133, v96, v97
	v_mul_f32_e32 v97, v4, v156
	v_rcp_f32_e32 v99, v99
	v_fmac_f32_e32 v110, v31, v206
	v_fmac_f32_e32 v97, v0, v148
	v_fmac_f32_e32 v110, v35, v143
	v_fmac_f32_e32 v97, v8, v227
	v_add_f32_e32 v135, v39, v110
	v_fmac_f32_e32 v97, v12, v231
	v_mul_f32_e32 v110, 0xbfb8aa3b, v135
	v_add_f32_e32 v97, v16, v97
	v_exp_f32_e32 v136, v110
	v_mul_f32_e32 v110, v98, v99
	v_mul_f32_e32 v99, 0xbfb8aa3b, v97
	v_mul_f32_e32 v98, v109, v111
	v_exp_f32_e32 v109, v99
	v_mul_f32_e32 v99, v5, v157
	v_fmac_f32_e32 v99, v1, v149
	v_fmac_f32_e32 v99, v9, v228
	v_fmac_f32_e32 v99, v13, v144
	v_add_f32_e32 v96, 1.0, v136
	v_add_f32_e32 v136, v17, v99
	v_mul_f32_e32 v99, 0xbfb8aa3b, v136
	v_rcp_f32_e32 v96, v96
	v_exp_f32_e32 v111, v99
	v_mul_f32_e32 v137, v7, v159
	v_fmac_f32_e32 v137, v3, v151
	v_mul_f32_e32 v99, v135, v96
	v_add_f32_e32 v96, 1.0, v109
	v_add_f32_e32 v109, 1.0, v111
	v_mul_f32_e32 v111, v6, v158
	v_fmac_f32_e32 v111, v2, v150
	v_fmac_f32_e32 v111, v10, v229
	v_fmac_f32_e32 v111, v14, v232
	v_add_f32_e32 v135, v18, v111
	v_mul_f32_e32 v111, 0xbfb8aa3b, v135
	v_exp_f32_e32 v111, v111
	v_fmac_f32_e32 v137, v11, v139
	v_fmac_f32_e32 v137, v15, v233
	v_add_f32_e32 v137, v19, v137
	v_mul_f32_e32 v138, 0xbfb8aa3b, v137
	v_exp_f32_e32 v138, v138
	v_add_f32_e32 v111, 1.0, v111
	v_rcp_f32_e32 v96, v96
	v_rcp_f32_e32 v145, v111
	v_add_f32_e32 v111, 1.0, v138
	v_rcp_f32_e32 v138, v111
	v_mul_f32_e32 v111, v97, v96
	v_mul_f32_e32 v97, v135, v145
	s_waitcnt vmcnt(11)
	v_lshlrev_b32_e32 v145, 16, v92
	v_and_b32_e32 v146, 0xffff0000, v92
	v_mul_f32_e32 v92, v24, v160
	v_fmac_f32_e32 v92, v20, v152
	v_fmac_f32_e32 v92, v28, v140
	v_fmac_f32_e32 v92, v32, v145
	v_mul_f32_e32 v135, v26, v195
	v_rcp_f32_e32 v109, v109
	v_add_f32_e32 v92, v36, v92
	v_fmac_f32_e32 v135, v22, v154
	v_lshlrev_b32_e32 v148, 16, v93
	v_and_b32_e32 v149, 0xffff0000, v93
	v_lshlrev_b32_e32 v234, 16, v94
	v_mul_f32_e32 v93, 0xbfb8aa3b, v92
	v_and_b32_e32 v235, 0xffff0000, v94
	v_mul_f32_e32 v94, v25, v161
	v_fmac_f32_e32 v135, v30, v142
	v_exp_f32_e32 v93, v93
	v_fmac_f32_e32 v94, v21, v153
	v_fmac_f32_e32 v135, v34, v148
	v_fmac_f32_e32 v94, v29, v141
	v_add_f32_e32 v135, v38, v135
	v_mul_f32_e32 v109, v136, v109
	v_fmac_f32_e32 v94, v33, v146
	v_mul_f32_e32 v136, 0xbfb8aa3b, v135
	v_add_f32_e32 v94, v37, v94
	v_exp_f32_e32 v136, v136
	v_lshlrev_b32_e32 v237, 16, v95
	v_and_b32_e32 v239, 0xffff0000, v95
	v_add_f32_e32 v93, 1.0, v93
	v_mul_f32_e32 v95, 0xbfb8aa3b, v94
	v_exp_f32_e32 v95, v95
	v_rcp_f32_e32 v93, v93
	v_add_f32_e32 v136, 1.0, v136
	v_mul_f32_e32 v96, v137, v138
	v_rcp_f32_e32 v137, v136
	v_mul_f32_e32 v136, v27, v206
	v_add_f32_e32 v95, 1.0, v95
	v_fmac_f32_e32 v136, v23, v155
	v_mul_f32_e32 v138, v92, v93
	v_mul_f32_e32 v93, v4, v227
	v_rcp_f32_e32 v95, v95
	v_fmac_f32_e32 v136, v31, v143
	v_fmac_f32_e32 v93, v0, v156
	v_fmac_f32_e32 v136, v35, v149
	v_fmac_f32_e32 v93, v8, v231
	v_add_f32_e32 v147, v39, v136
	v_fmac_f32_e32 v93, v12, v234
	v_mul_f32_e32 v136, 0xbfb8aa3b, v147
	v_add_f32_e32 v93, v16, v93
	v_exp_f32_e32 v150, v136
	v_mul_f32_e32 v136, v94, v95
	v_mul_f32_e32 v95, 0xbfb8aa3b, v93
	v_mul_f32_e32 v94, v135, v137
	v_exp_f32_e32 v135, v95
	v_mul_f32_e32 v95, v5, v228
	v_fmac_f32_e32 v95, v1, v157
	v_fmac_f32_e32 v95, v9, v144
	v_fmac_f32_e32 v95, v13, v235
	v_add_f32_e32 v92, 1.0, v150
	v_add_f32_e32 v150, v17, v95
	v_mul_f32_e32 v95, 0xbfb8aa3b, v150
	v_rcp_f32_e32 v92, v92
	v_exp_f32_e32 v137, v95
	v_mul_f32_e32 v151, v7, v139
	v_fmac_f32_e32 v151, v3, v159
	v_mul_f32_e32 v95, v147, v92
	v_add_f32_e32 v92, 1.0, v135
	v_add_f32_e32 v135, 1.0, v137
	v_mul_f32_e32 v137, v6, v229
	v_fmac_f32_e32 v137, v2, v158
	v_fmac_f32_e32 v137, v10, v232
	v_fmac_f32_e32 v137, v14, v237
	v_add_f32_e32 v147, v18, v137
	v_mul_f32_e32 v137, 0xbfb8aa3b, v147
	v_exp_f32_e32 v137, v137
	v_fmac_f32_e32 v151, v11, v233
	v_fmac_f32_e32 v151, v15, v239
	v_add_f32_e32 v151, v19, v151
	v_mul_f32_e32 v152, 0xbfb8aa3b, v151
	v_exp_f32_e32 v152, v152
	v_add_f32_e32 v137, 1.0, v137
	s_waitcnt vmcnt(10)
; template <bool WITH_C, bool B_TR>
; __device__ __forceinline__ void ssd_stage(const Params& p, LAS unsigned char* lds, int b, int c, int g) {
;     ...
;         for (int tt = 0; tt < 16; ++tt) rows[3 + tt] = *(const u32x4*)(src + (size_t)tt * D_XBC);
;         float u1[8], u2[8], u3[8];
;         unpack8(rows[0], u3); unpack8(rows[1], u2); unpack8(rows[2], u1);
; #pragma unroll
;         for (int hb = 0; hb < 2; ++hb) {
;             float y[8][8];
; #pragma unroll
;             for (int tt = 0; tt < 8; ++tt) {
;                 float u0[8]; unpack8(rows[3 + 8 * hb + tt], u0);
; #pragma unroll
;                 for (int i = 0; i < 8; ++i) { const float a = w0[i] * u3[i] + w1[i] * u2[i] + w2[i] * u1[i] + w3[i] * u0[i] + bs[i]; y[tt][i] = a * __builtin_amdgcn_rcpf(1.f + __expf(-a)); u3[i] = u2[i]; u2[i] = u1[i]; u1[i] = u0[i]; }
	v_lshlrev_b32_e32 v241, 16, v89
	v_and_b32_e32 v242, 0xffff0000, v89
	v_mul_f32_e32 v89, v24, v140
	v_rcp_f32_e32 v92, v92
	v_rcp_f32_e32 v153, v137
	v_fmac_f32_e32 v89, v20, v160
	v_lshlrev_b32_e32 v240, 16, v88
	v_fmac_f32_e32 v89, v28, v145
	v_fmac_f32_e32 v89, v32, v240
	v_add_f32_e32 v137, 1.0, v152
	v_add_f32_e32 v89, v36, v89
	v_rcp_f32_e32 v152, v137
	v_mul_f32_e32 v137, v93, v92
	v_mul_f32_e32 v93, v147, v153
	v_mul_f32_e32 v147, 0xbfb8aa3b, v89
	v_exp_f32_e32 v147, v147
	v_lshlrev_b32_e32 v245, 16, v91
	v_and_b32_e32 v247, 0xffff0000, v91
	v_rcp_f32_e32 v135, v135
	v_add_f32_e32 v91, 1.0, v147
	v_mul_f32_e32 v147, v25, v141
	v_fmac_f32_e32 v147, v21, v161
	v_and_b32_e32 v88, 0xffff0000, v88
	v_fmac_f32_e32 v147, v29, v146
	v_fmac_f32_e32 v147, v33, v88
	v_add_f32_e32 v147, v37, v147
	v_mul_f32_e32 v135, v150, v135
	v_mul_f32_e32 v92, v151, v152
	v_mul_f32_e32 v150, 0xbfb8aa3b, v147
	v_mul_f32_e32 v151, v26, v142
	v_exp_f32_e32 v150, v150
	v_fmac_f32_e32 v151, v22, v195
	v_fmac_f32_e32 v151, v30, v148
	v_fmac_f32_e32 v151, v34, v241
	v_add_f32_e32 v151, v38, v151
	v_mul_f32_e32 v152, 0xbfb8aa3b, v151
	v_add_f32_e32 v150, 1.0, v150
	v_mul_f32_e32 v153, v27, v143
	v_exp_f32_e32 v152, v152
	v_rcp_f32_e32 v91, v91
	v_rcp_f32_e32 v150, v150
	v_fmac_f32_e32 v153, v23, v206
	v_fmac_f32_e32 v153, v31, v149
	v_fmac_f32_e32 v153, v35, v242
	v_add_f32_e32 v153, v39, v153
	v_add_f32_e32 v152, 1.0, v152
	v_mul_f32_e32 v154, 0xbfb8aa3b, v153
	v_mul_f32_e32 v157, v89, v91
	v_mul_f32_e32 v155, v147, v150
	v_mul_f32_e32 v91, v4, v231
	v_mul_f32_e32 v150, v5, v144
	v_rcp_f32_e32 v152, v152
	v_exp_f32_e32 v154, v154
	v_fmac_f32_e32 v91, v0, v227
	v_fmac_f32_e32 v150, v1, v228
	v_lshlrev_b32_e32 v243, 16, v90
	v_and_b32_e32 v90, 0xffff0000, v90
	v_fmac_f32_e32 v91, v8, v234
	v_fmac_f32_e32 v150, v9, v235
	v_fmac_f32_e32 v91, v12, v243
	v_fmac_f32_e32 v150, v13, v90
	v_add_f32_e32 v91, v16, v91
	v_add_f32_e32 v150, v17, v150
	v_mul_f32_e32 v152, v151, v152
	v_add_f32_e32 v89, 1.0, v154
	v_mul_f32_e32 v147, 0xbfb8aa3b, v91
	v_mul_f32_e32 v151, 0xbfb8aa3b, v150
	v_rcp_f32_e32 v89, v89
	v_exp_f32_e32 v147, v147
	v_exp_f32_e32 v151, v151
	v_mul_f32_e32 v156, v7, v233
	v_mul_f32_e32 v153, v153, v89
	v_add_f32_e32 v89, 1.0, v147
	v_add_f32_e32 v147, 1.0, v151
	v_mul_f32_e32 v151, v6, v232
	v_fmac_f32_e32 v151, v2, v229
	v_fmac_f32_e32 v151, v10, v237
	v_fmac_f32_e32 v156, v3, v139
	v_fmac_f32_e32 v151, v14, v245
	v_fmac_f32_e32 v156, v11, v239
	v_add_f32_e32 v151, v18, v151
	v_fmac_f32_e32 v156, v15, v247
	v_mul_f32_e32 v154, 0xbfb8aa3b, v151
	v_add_f32_e32 v139, v19, v156
	v_exp_f32_e32 v154, v154
	v_mul_f32_e32 v156, 0xbfb8aa3b, v139
	s_waitcnt vmcnt(9)
	v_lshlrev_b32_e32 v195, 16, v84
	v_and_b32_e32 v206, 0xffff0000, v84
	v_lshlrev_b32_e32 v250, 16, v86
	v_mul_f32_e32 v84, v24, v145
	v_and_b32_e32 v251, 0xffff0000, v86
	v_mul_f32_e32 v86, v25, v146
	v_rcp_f32_e32 v89, v89
	v_exp_f32_e32 v156, v156
	v_fmac_f32_e32 v84, v20, v140
	v_fmac_f32_e32 v86, v21, v141
	v_fmac_f32_e32 v84, v28, v240
	v_fmac_f32_e32 v86, v29, v88
	v_fmac_f32_e32 v84, v32, v195
	v_fmac_f32_e32 v86, v33, v206
	v_add_f32_e32 v154, 1.0, v154
	v_add_f32_e32 v84, v36, v84
	v_add_f32_e32 v86, v37, v86
	v_rcp_f32_e32 v158, v154
	v_add_f32_e32 v154, 1.0, v156
	v_mul_f32_e32 v156, v91, v89
	v_lshlrev_b32_e32 v248, 16, v85
	v_and_b32_e32 v249, 0xffff0000, v85
	v_mul_f32_e32 v85, 0xbfb8aa3b, v84
	v_lshlrev_b32_e32 v207, 16, v87
	v_and_b32_e32 v208, 0xffff0000, v87
	v_mul_f32_e32 v87, 0xbfb8aa3b, v86
	v_mul_f32_e32 v89, v26, v148
	v_rcp_f32_e32 v147, v147
	v_rcp_f32_e32 v159, v154
	v_exp_f32_e32 v85, v85
	v_exp_f32_e32 v87, v87
	v_fmac_f32_e32 v89, v22, v142
	v_fmac_f32_e32 v89, v30, v241
	v_fmac_f32_e32 v89, v34, v248
	v_add_f32_e32 v89, v38, v89
	v_mul_f32_e32 v154, v150, v147
	v_mul_f32_e32 v150, v139, v159
	v_add_f32_e32 v85, 1.0, v85
	v_mul_f32_e32 v91, 0xbfb8aa3b, v89
	v_add_f32_e32 v87, 1.0, v87
	v_mul_f32_e32 v139, v27, v149
	v_exp_f32_e32 v91, v91
	v_rcp_f32_e32 v85, v85
	v_rcp_f32_e32 v87, v87
	v_fmac_f32_e32 v139, v23, v143
	v_fmac_f32_e32 v139, v31, v242
	v_fmac_f32_e32 v139, v35, v249
	v_add_f32_e32 v139, v39, v139
	v_add_f32_e32 v91, 1.0, v91
	v_mul_f32_e32 v140, 0xbfb8aa3b, v139
	v_mul_f32_e32 v230, v84, v85
	v_mul_f32_e32 v228, v86, v87
	v_mul_f32_e32 v85, v4, v234
	v_mul_f32_e32 v87, v5, v235
	v_rcp_f32_e32 v91, v91
	v_exp_f32_e32 v140, v140
	v_fmac_f32_e32 v85, v0, v231
	v_fmac_f32_e32 v87, v1, v144
	v_fmac_f32_e32 v85, v8, v243
	v_fmac_f32_e32 v87, v9, v90
	v_fmac_f32_e32 v85, v12, v250
	v_fmac_f32_e32 v87, v13, v251
	v_add_f32_e32 v85, v16, v85
	v_add_f32_e32 v87, v17, v87
	v_mul_f32_e32 v160, v89, v91
	v_add_f32_e32 v84, 1.0, v140
	v_mul_f32_e32 v86, 0xbfb8aa3b, v85
	v_mul_f32_e32 v89, 0xbfb8aa3b, v87
	v_rcp_f32_e32 v84, v84
	v_exp_f32_e32 v86, v86
	v_exp_f32_e32 v89, v89
	s_waitcnt vmcnt(8)
; template <bool WITH_C, bool B_TR>
; __device__ __forceinline__ void ssd_stage(const Params& p, LAS unsigned char* lds, int b, int c, int g) {
;     ...
;         for (int tt = 0; tt < 16; ++tt) rows[3 + tt] = *(const u32x4*)(src + (size_t)tt * D_XBC);
;         float u1[8], u2[8], u3[8];
;         unpack8(rows[0], u3); unpack8(rows[1], u2); unpack8(rows[2], u1);
; #pragma unroll
;         for (int hb = 0; hb < 2; ++hb) {
;             float y[8][8];
; #pragma unroll
;             for (int tt = 0; tt < 8; ++tt) {
;                 float u0[8]; unpack8(rows[3 + 8 * hb + tt], u0);
; #pragma unroll
;                 for (int i = 0; i < 8; ++i) { const float a = w0[i] * u3[i] + w1[i] * u2[i] + w2[i] * u1[i] + w3[i] * u0[i] + bs[i]; y[tt][i] = a * __builtin_amdgcn_rcpf(1.f + __expf(-a)); u3[i] = u2[i]; u2[i] = u1[i]; u1[i] = u0[i]; }
	v_lshlrev_b32_e32 v147, 16, v80
	v_mul_f32_e32 v161, v139, v84
	v_add_f32_e32 v84, 1.0, v86
	v_add_f32_e32 v86, 1.0, v89
	v_mul_f32_e32 v89, v6, v237
	v_fmac_f32_e32 v89, v2, v232
	v_fmac_f32_e32 v89, v10, v245
	v_fmac_f32_e32 v89, v14, v207
	v_add_f32_e32 v89, v18, v89
	v_rcp_f32_e32 v84, v84
	v_mul_f32_e32 v91, 0xbfb8aa3b, v89
	v_and_b32_e32 v144, 0xffff0000, v80
	v_mul_f32_e32 v80, v24, v240
	v_exp_f32_e32 v91, v91
	v_fmac_f32_e32 v80, v20, v145
	v_fmac_f32_e32 v80, v28, v195
	v_fmac_f32_e32 v80, v32, v147
	v_mul_f32_e32 v229, v85, v84
	v_add_f32_e32 v84, v36, v80
	v_mul_f32_e32 v139, v7, v239
	v_add_f32_e32 v91, 1.0, v91
	v_mul_f32_e32 v80, 0xbfb8aa3b, v84
	v_fmac_f32_e32 v139, v3, v233
	v_rcp_f32_e32 v91, v91
	v_exp_f32_e32 v85, v80
	v_fmac_f32_e32 v139, v11, v247
	v_fmac_f32_e32 v139, v15, v208
	v_add_f32_e32 v139, v19, v139
	v_mul_f32_e32 v140, 0xbfb8aa3b, v139
	v_mul_f32_e32 v159, v89, v91
	v_lshlrev_b32_e32 v141, 16, v81
	v_and_b32_e32 v91, 0xffff0000, v81
	v_lshlrev_b32_e32 v81, 16, v83
	v_and_b32_e32 v80, 0xffff0000, v83
	v_add_f32_e32 v83, 1.0, v85
	v_mul_f32_e32 v85, v25, v88
	v_exp_f32_e32 v140, v140
	v_rcp_f32_e32 v86, v86
	v_fmac_f32_e32 v85, v21, v146
	v_fmac_f32_e32 v85, v29, v206
	v_fmac_f32_e32 v85, v33, v144
	v_add_f32_e32 v85, v37, v85
	v_add_f32_e32 v140, 1.0, v140
	v_mul_f32_e32 v227, v87, v86
	v_mul_f32_e32 v87, 0xbfb8aa3b, v85
	v_mul_f32_e32 v89, v26, v241
	v_rcp_f32_e32 v140, v140
	v_exp_f32_e32 v87, v87
	v_fmac_f32_e32 v89, v22, v148
	v_fmac_f32_e32 v89, v30, v248
	v_fmac_f32_e32 v89, v34, v141
	v_add_f32_e32 v89, v38, v89
	v_mul_f32_e32 v151, v151, v158
	v_mul_f32_e32 v158, v139, v140
	v_mul_f32_e32 v139, 0xbfb8aa3b, v89
	v_add_f32_e32 v87, 1.0, v87
	v_mul_f32_e32 v140, v27, v242
	v_exp_f32_e32 v139, v139
	v_rcp_f32_e32 v83, v83
	v_rcp_f32_e32 v87, v87
	v_fmac_f32_e32 v140, v23, v149
	v_fmac_f32_e32 v140, v31, v249
	v_fmac_f32_e32 v140, v35, v91
	v_add_f32_e32 v140, v39, v140
	v_add_f32_e32 v139, 1.0, v139
	v_mul_f32_e32 v142, 0xbfb8aa3b, v140
	v_mul_f32_e32 v238, v84, v83
	v_mul_f32_e32 v236, v85, v87
	v_mul_f32_e32 v84, v4, v243
	v_mul_f32_e32 v87, v5, v90
	v_rcp_f32_e32 v139, v139
	v_exp_f32_e32 v142, v142
	v_fmac_f32_e32 v84, v0, v234
	v_fmac_f32_e32 v87, v1, v235
	v_lshlrev_b32_e32 v86, 16, v82
	v_and_b32_e32 v82, 0xffff0000, v82
	v_fmac_f32_e32 v84, v8, v250
	v_fmac_f32_e32 v87, v9, v251
	v_fmac_f32_e32 v84, v12, v86
	v_fmac_f32_e32 v87, v13, v82
	v_add_f32_e32 v84, v16, v84
	v_add_f32_e32 v87, v17, v87
	v_mul_f32_e32 v233, v89, v139
	v_add_f32_e32 v83, 1.0, v142
	v_mul_f32_e32 v85, 0xbfb8aa3b, v84
	v_mul_f32_e32 v89, 0xbfb8aa3b, v87
	v_rcp_f32_e32 v83, v83
	v_exp_f32_e32 v85, v85
	v_exp_f32_e32 v89, v89
	v_add_co_u32_e32 v44, vcc, s44, v40
	v_mul_f32_e32 v234, v140, v83
	v_add_f32_e32 v83, 1.0, v85
	v_add_f32_e32 v85, 1.0, v89
	v_mul_f32_e32 v89, v6, v245
	v_fmac_f32_e32 v89, v2, v237
	v_fmac_f32_e32 v89, v10, v207
	v_fmac_f32_e32 v89, v14, v81
	v_addc_co_u32_e32 v45, vcc, 0, v41, vcc
	s_mov_b32 s44, 0xf000
	v_add_f32_e32 v89, v18, v89
	s_nop 0
	s_nop 0
	v_add_co_u32_e32 v42, vcc, s44, v40
	v_mul_f32_e32 v139, 0xbfb8aa3b, v89
	v_mul_f32_e32 v140, v7, v247
	v_addc_co_u32_e32 v43, vcc, 0, v41, vcc
	s_mov_b32 s44, 0x10000
	v_exp_f32_e32 v139, v139
	v_fmac_f32_e32 v140, v3, v239
	v_add_co_u32_e32 v44, vcc, s44, v40
	v_fmac_f32_e32 v140, v11, v208
	s_nop 0
	v_addc_co_u32_e32 v45, vcc, 0, v41, vcc
	s_mov_b32 s44, 0x12000
	v_fmac_f32_e32 v140, v15, v80
	s_nop 0
	s_nop 0
	v_add_co_u32_e32 v42, vcc, s44, v40
	v_add_f32_e32 v140, v19, v140
	s_nop 0
	v_addc_co_u32_e32 v43, vcc, 0, v41, vcc
	s_mov_b32 s44, 0x13000
	v_mul_f32_e32 v142, 0xbfb8aa3b, v140
	v_add_f32_e32 v139, 1.0, v139
	v_add_co_u32_e32 v44, vcc, s44, v40
	v_exp_f32_e32 v142, v142
	v_rcp_f32_e32 v85, v85
	v_rcp_f32_e32 v139, v139
	v_addc_co_u32_e32 v45, vcc, 0, v41, vcc
	s_mov_b32 s44, 0x15000
	s_nop 0
	s_nop 0
	v_add_co_u32_e32 v42, vcc, s44, v40
	s_mov_b32 s44, 0x16000
	s_nop 0
	v_addc_co_u32_e32 v43, vcc, 0, v41, vcc
	v_add_co_u32_e32 v40, vcc, s44, v40
	v_add_f32_e32 v142, 1.0, v142
	v_mul_f32_e32 v235, v87, v85
	v_mul_f32_e32 v232, v89, v139
	s_waitcnt vmcnt(7)
	v_lshlrev_b32_e32 v148, 16, v76
	v_and_b32_e32 v145, 0xffff0000, v76
	v_lshlrev_b32_e32 v87, 16, v78
	v_mul_f32_e32 v76, v24, v195
	v_and_b32_e32 v89, 0xffff0000, v78
	v_mul_f32_e32 v78, v25, v206
	v_addc_co_u32_e32 v41, vcc, 0, v41, vcc
	v_rcp_f32_e32 v83, v83
	v_rcp_f32_e32 v142, v142
	v_fmac_f32_e32 v76, v20, v240
	v_fmac_f32_e32 v78, v21, v88
	global_load_dwordx4 v[44:47], v[42:43], off
	s_nop 0
	global_load_dwordx4 v[40:43], v[40:41], off offset:2048
	v_fmac_f32_e32 v76, v28, v147
	v_fmac_f32_e32 v78, v29, v144
	v_fmac_f32_e32 v76, v32, v148
	v_fmac_f32_e32 v78, v33, v145
	v_add_f32_e32 v76, v36, v76
	v_add_f32_e32 v78, v37, v78
	v_mul_f32_e32 v237, v84, v83
	v_mul_f32_e32 v231, v140, v142
	v_lshlrev_b32_e32 v142, 16, v77
	v_and_b32_e32 v139, 0xffff0000, v77
	v_mul_f32_e32 v77, 0xbfb8aa3b, v76
	v_mul_f32_e32 v83, 0xbfb8aa3b, v78
	v_mul_f32_e32 v85, v26, v248
	v_exp_f32_e32 v77, v77
	v_exp_f32_e32 v83, v83
	v_fmac_f32_e32 v85, v22, v241
	v_fmac_f32_e32 v85, v30, v141
	v_fmac_f32_e32 v85, v34, v142
	v_add_f32_e32 v85, v38, v85
	v_add_f32_e32 v77, 1.0, v77
	v_mul_f32_e32 v88, 0xbfb8aa3b, v85
	v_add_f32_e32 v83, 1.0, v83
	v_mul_f32_e32 v140, v27, v249
	v_exp_f32_e32 v88, v88
	v_rcp_f32_e32 v77, v77
	v_rcp_f32_e32 v83, v83
	v_fmac_f32_e32 v140, v23, v242
	v_fmac_f32_e32 v140, v31, v91
	v_fmac_f32_e32 v140, v35, v139
	v_add_f32_e32 v140, v39, v140
	v_add_f32_e32 v88, 1.0, v88
	v_mul_f32_e32 v143, 0xbfb8aa3b, v140
	v_mul_f32_e32 v246, v76, v77
	v_mul_f32_e32 v244, v78, v83
	v_mul_f32_e32 v77, v4, v250
	v_mul_f32_e32 v83, v5, v251
	v_rcp_f32_e32 v88, v88
	v_exp_f32_e32 v143, v143
	v_fmac_f32_e32 v77, v0, v243
	v_fmac_f32_e32 v83, v1, v90
	v_fmac_f32_e32 v77, v8, v86
	v_fmac_f32_e32 v83, v9, v82
	v_fmac_f32_e32 v77, v12, v87
	v_fmac_f32_e32 v83, v13, v89
	v_add_f32_e32 v77, v16, v77
	v_add_f32_e32 v83, v17, v83
	v_mul_f32_e32 v241, v85, v88
	v_add_f32_e32 v76, 1.0, v143
	v_mul_f32_e32 v78, 0xbfb8aa3b, v77
	v_mul_f32_e32 v85, 0xbfb8aa3b, v83
	v_rcp_f32_e32 v76, v76
	v_exp_f32_e32 v78, v78
	v_exp_f32_e32 v85, v85
	v_mul_f32_e32 v90, v7, v208
	v_mul_f32_e32 v242, v140, v76
	v_add_f32_e32 v76, 1.0, v78
	v_add_f32_e32 v78, 1.0, v85
	v_mul_f32_e32 v85, v6, v207
	v_fmac_f32_e32 v85, v2, v245
	v_fmac_f32_e32 v90, v3, v247
	v_lshlrev_b32_e32 v84, 16, v79
	v_and_b32_e32 v79, 0xffff0000, v79
	v_fmac_f32_e32 v85, v10, v81
	v_fmac_f32_e32 v90, v11, v80
	v_fmac_f32_e32 v85, v14, v84
	v_fmac_f32_e32 v90, v15, v79
	v_add_f32_e32 v85, v18, v85
	v_add_f32_e32 v90, v19, v90
	v_mul_f32_e32 v88, 0xbfb8aa3b, v85
	v_mul_f32_e32 v140, 0xbfb8aa3b, v90
	v_exp_f32_e32 v88, v88
	v_exp_f32_e32 v140, v140
	s_waitcnt vmcnt(8)
; #define LAS __attribute__((address_space(3)))
; __device__ __forceinline__ unsigned cvt_pk_bf16(float lo, float hi) { unsigned r; asm volatile("v_cvt_pk_bf16_f32 %0, %1, %2" : "=v"(r) : "v"(lo), "v"(hi)); return r; }
; template <bool WITH_C, bool B_TR>
; __device__ __forceinline__ void ssd_stage(const Params& p, LAS unsigned char* lds, int b, int c, int g) {
;     ...
;                 for (int i = 0; i < 8; ++i) { const float a = w0[i] * u3[i] + w1[i] * u2[i] + w2[i] * u1[i] + w3[i] * u0[i] + bs[i]; y[tt][i] = a * __builtin_amdgcn_rcpf(1.f + __expf(-a)); u3[i] = u2[i]; u2[i] = u1[i]; u1[i] = u0[i]; }
;             }
;             const bool tr = (kind == 0) || (kind == 1 && B_TR);
;             if (tr) {
;                 LAS unsigned char* img = lds + (kind == 0 ? SSD_XT : SSD_B);
;                 const int r0 = kind == 0 ? 8 * cg : 8 * (cg - 64);
; #pragma unroll
;                 for (int i = 0; i < 8; ++i) { u32x4 w; w.x = pg8::cvt_pk_bf16(y[0][i], y[1][i]); w.y = pg8::cvt_pk_bf16(y[2][i], y[3][i]); w.z = pg8::cvt_pk_bf16(y[4][i], y[5][i]); w.w = pg8::cvt_pk_bf16(y[6][i], y[7][i]);
;                     *(LAS u32x4*)(img + ((r0 + i) * 72 + 16 * seg + 8 * hb) * 2) = w; }
;             } else {
;                 LAS unsigned char* img = lds + (kind == 1 ? SSD_B : SSD_C);
;                 const int c0 = kind == 1 ? 8 * (cg - 64) : 8 * (cg - 80);
; #pragma unroll
;                 for (int tt = 0; tt < 8; ++tt) { u32x4 w; w.x = pg8::cvt_pk_bf16(y[tt][0], y[tt][1]); w.y = pg8::cvt_pk_bf16(y[tt][2], y[tt][3]); w.z = pg8::cvt_pk_bf16(y[tt][4], y[tt][5]); w.w = pg8::cvt_pk_bf16(y[tt][6], y[tt][7]);
;                     *(LAS u32x4*)(img + ((16 * seg + 8 * hb + tt) * 136 + c0) * 2) = w; }
	v_lshlrev_b32_e32 v149, 16, v72
	v_and_b32_e32 v146, 0xffff0000, v72
	v_add_f32_e32 v88, 1.0, v88
	v_add_f32_e32 v140, 1.0, v140
	v_rcp_f32_e32 v88, v88
	v_rcp_f32_e32 v140, v140
	v_mul_f32_e32 v72, v24, v147
	v_rcp_f32_e32 v76, v76
	v_mul_f32_e32 v240, v85, v88
	v_mul_f32_e32 v239, v90, v140
	v_lshlrev_b32_e32 v88, 16, v74
	v_and_b32_e32 v90, 0xffff0000, v74
	v_mul_f32_e32 v74, v25, v144
	v_rcp_f32_e32 v78, v78
	v_fmac_f32_e32 v72, v20, v195
	v_fmac_f32_e32 v74, v21, v206
	v_fmac_f32_e32 v72, v28, v148
	v_fmac_f32_e32 v74, v29, v145
	v_fmac_f32_e32 v72, v32, v149
	v_fmac_f32_e32 v74, v33, v146
	v_add_f32_e32 v72, v36, v72
	v_add_f32_e32 v74, v37, v74
	v_mul_f32_e32 v245, v77, v76
	v_mul_f32_e32 v243, v83, v78
	v_lshlrev_b32_e32 v143, 16, v73
	v_and_b32_e32 v140, 0xffff0000, v73
	v_mul_f32_e32 v73, 0xbfb8aa3b, v72
	v_lshlrev_b32_e32 v85, 16, v75
	v_and_b32_e32 v83, 0xffff0000, v75
	v_mul_f32_e32 v75, 0xbfb8aa3b, v74
	v_mul_f32_e32 v76, v26, v141
	v_exp_f32_e32 v73, v73
	v_exp_f32_e32 v75, v75
	v_fmac_f32_e32 v76, v22, v248
	v_fmac_f32_e32 v76, v30, v142
	v_fmac_f32_e32 v76, v34, v143
	v_add_f32_e32 v76, v38, v76
	v_add_f32_e32 v73, 1.0, v73
	v_mul_f32_e32 v77, 0xbfb8aa3b, v76
	v_add_f32_e32 v75, 1.0, v75
	v_mul_f32_e32 v78, v27, v91
	v_exp_f32_e32 v77, v77
	v_rcp_f32_e32 v73, v73
	v_rcp_f32_e32 v75, v75
	v_fmac_f32_e32 v78, v23, v249
	v_fmac_f32_e32 v78, v31, v139
	v_fmac_f32_e32 v78, v35, v140
	v_add_f32_e32 v78, v39, v78
	v_add_f32_e32 v77, 1.0, v77
	v_mul_f32_e32 v195, 0xbfb8aa3b, v78
	v_mul_f32_e32 v206, v72, v73
	v_mul_f32_e32 v252, v74, v75
	v_mul_f32_e32 v73, v4, v86
	v_mul_f32_e32 v75, v5, v82
	v_rcp_f32_e32 v77, v77
	v_exp_f32_e32 v195, v195
	v_fmac_f32_e32 v73, v0, v250
	v_fmac_f32_e32 v75, v1, v251
	v_fmac_f32_e32 v73, v8, v87
	v_fmac_f32_e32 v75, v9, v89
	v_fmac_f32_e32 v73, v12, v88
	v_fmac_f32_e32 v75, v13, v90
	v_add_f32_e32 v73, v16, v73
	v_add_f32_e32 v75, v17, v75
	v_mul_f32_e32 v249, v76, v77
	v_add_f32_e32 v72, 1.0, v195
	v_mul_f32_e32 v74, 0xbfb8aa3b, v73
	v_mul_f32_e32 v76, 0xbfb8aa3b, v75
	v_rcp_f32_e32 v72, v72
	v_exp_f32_e32 v74, v74
	v_exp_f32_e32 v76, v76
	s_movk_i32 s42, 0x88
	v_mul_f32_e32 v250, v78, v72
	v_add_f32_e32 v72, 1.0, v74
	v_add_f32_e32 v74, 1.0, v76
	v_mul_f32_e32 v76, v6, v81
	v_fmac_f32_e32 v76, v2, v207
	v_mul_f32_e32 v78, v7, v80
	v_fmac_f32_e32 v76, v10, v84
	v_fmac_f32_e32 v78, v3, v208
	v_fmac_f32_e32 v76, v14, v85
	v_fmac_f32_e32 v78, v11, v79
	v_add_f32_e32 v76, v18, v76
	v_fmac_f32_e32 v78, v15, v83
	v_mul_f32_e32 v77, 0xbfb8aa3b, v76
	v_add_f32_e32 v78, v19, v78
	v_exp_f32_e32 v77, v77
	v_mul_f32_e32 v195, 0xbfb8aa3b, v78
	v_exp_f32_e32 v195, v195
	v_rcp_f32_e32 v72, v72
	v_add_f32_e32 v77, 1.0, v77
	v_rcp_f32_e32 v77, v77
	v_add_f32_e32 v195, 1.0, v195
	v_rcp_f32_e32 v74, v74
	v_rcp_f32_e32 v207, v195
	v_add_u32_e32 v100, 0, v100
	v_mul_f32_e32 v248, v76, v77
	v_mad_u32_u24 v76, v131, s42, v134
	v_mul_f32_e32 v195, v73, v72
	v_mul_f32_e32 v251, v75, v74
	v_mul_f32_e32 v247, v78, v207
	v_lshl_add_u32 v77, v76, 1, v100
	s_and_saveexec_b64 s[42:43], s[40:41]
	s_xor_b64 s[42:43], exec, s[42:43]
	s_cbranch_execz .LBB0_865
	v_cvt_pk_bf16_f32 v72, v108, v106
	v_cvt_pk_bf16_f32 v73, v103, v104
	v_cvt_pk_bf16_f32 v74, v107, v105
	v_cvt_pk_bf16_f32 v75, v102, v101
	ds_write_b128 v77, v[72:75]
	v_cvt_pk_bf16_f32 v72, v133, v110
	v_cvt_pk_bf16_f32 v73, v98, v99
	v_cvt_pk_bf16_f32 v74, v111, v109
	v_cvt_pk_bf16_f32 v75, v97, v96
	ds_write_b128 v77, v[72:75] offset:272
	v_cvt_pk_bf16_f32 v72, v138, v136
	v_cvt_pk_bf16_f32 v73, v94, v95
	v_cvt_pk_bf16_f32 v74, v137, v135
	v_cvt_pk_bf16_f32 v75, v93, v92
	ds_write_b128 v77, v[72:75] offset:544
	v_cvt_pk_bf16_f32 v72, v157, v155
	v_cvt_pk_bf16_f32 v73, v152, v153
	v_cvt_pk_bf16_f32 v74, v156, v154
	v_cvt_pk_bf16_f32 v75, v151, v150
	ds_write_b128 v77, v[72:75] offset:816
	v_cvt_pk_bf16_f32 v72, v230, v228
	v_cvt_pk_bf16_f32 v73, v160, v161
	v_cvt_pk_bf16_f32 v74, v229, v227
	v_cvt_pk_bf16_f32 v75, v159, v158
	ds_write_b128 v77, v[72:75] offset:1088
	v_cvt_pk_bf16_f32 v72, v238, v236
	v_cvt_pk_bf16_f32 v73, v233, v234
	v_cvt_pk_bf16_f32 v74, v237, v235
	v_cvt_pk_bf16_f32 v75, v232, v231
	ds_write_b128 v77, v[72:75] offset:1360
	v_cvt_pk_bf16_f32 v72, v246, v244
	v_cvt_pk_bf16_f32 v73, v241, v242
	v_cvt_pk_bf16_f32 v74, v245, v243
	v_cvt_pk_bf16_f32 v75, v240, v239
	ds_write_b128 v77, v[72:75] offset:1632
	v_cvt_pk_bf16_f32 v72, v206, v252
	v_cvt_pk_bf16_f32 v73, v249, v250
	v_cvt_pk_bf16_f32 v74, v195, v251
	v_cvt_pk_bf16_f32 v75, v248, v247
	v_add_u32_e32 v134, 0x3b8, v76

; #define LAS __attribute__((address_space(3)))
; __device__ __forceinline__ int otid() { int t = threadIdx.x; asm volatile("" : "+v"(t)); return t; }
; __device__ __forceinline__ float softplusf_(float x) { return fmaxf(x, 0.f) + log1pf(__expf(-fabsf(x))); }
; __device__ __forceinline__ void ssd_dt(const Params& p, LAS unsigned char* lds, int b, int c, int g) {
;     const int lane = otid() & 63, e = otid() >> 6, eg = 8 * g + e;
;     const float* SM = (const float*)(p.ws + WS_SM);
;     const float dt = softplusf_(SM[((size_t)b * SEQ + 64 * c + lane) * 256 + eg] + p.in[I_DTB][eg]);
;     float a = dt * -__expf(p.in[I_ALOG][eg]);
; #pragma unroll
;     for (int o = 1; o < 64; o <<= 1) { const float t = __shfl_up(a, o); if (lane >= o) a += t; }
;     ((LAS float*)(lds + SSD_ACS))[lane * 8 + e] = a; ((LAS float*)(lds + SSD_DT))[lane * 8 + e] = dt;
.LBB0_872:
	s_or_b64 exec, exec, s[58:59]
	v_mov_b32_e32 v0, v194
	v_mov_b32_e32 v1, v194
	s_lshl_b32 s41, s56, 3
	s_or_b32 s40, s60, s48
	v_and_b32_e32 v0, 63, v0
	v_ashrrev_i32_e32 v1, 6, v1
	v_add_u32_e32 v2, s41, v1
	v_or_b32_e32 v4, s40, v0
	v_mov_b32_e32 v5, s61
	v_readlane_b32 s42, v253, 45
	v_ashrrev_i32_e32 v3, 31, v2
	v_lshlrev_b64 v[4:5], 10, v[4:5]
	v_readlane_b32 s43, v253, 46
	v_lshlrev_b64 v[6:7], 2, v[2:3]
	v_readlane_b32 s80, v253, 4
	v_lshl_add_u64 v[4:5], s[42:43], 0, v[4:5]
	v_lshl_add_u64 v[2:3], v[4:5], 0, v[6:7]
	v_readlane_b32 s90, v253, 14
	v_readlane_b32 s91, v253, 15
	global_load_dword v4, v[2:3], off
	v_add_u32_e32 v68, s41, v113
	v_lshl_add_u64 v[2:3], s[90:91], 0, v[6:7]
	global_load_dword v2, v[2:3], off
	s_mov_b32 s41, 0xbfb8aa3b
	v_readlane_b32 s92, v253, 16
	v_readlane_b32 s93, v253, 17
	s_nop 0
	v_lshl_add_u64 v[248:249], s[92:93], 0, v[6:7]
	global_load_dword v250, v[248:249], off
	v_and_b32_e32 v227, 64, v198
	s_lshl_b64 s[42:43], s[66:67], 12
	s_lshl_b32 s33, s33, 5
	s_or_b32 s42, s42, s33
	v_ashrrev_i32_e32 v69, 31, v68
	v_mov_b32_e32 v129, v115
	v_mov_b32_e32 v131, v115
	v_mov_b32_e32 v133, v115
	v_readlane_b32 s94, v253, 18
	v_readlane_b32 s95, v253, 19
	v_readlane_b32 s81, v253, 5
	v_readlane_b32 s82, v253, 6
	v_readlane_b32 s83, v253, 7
	v_readlane_b32 s84, v253, 8
	v_readlane_b32 s85, v253, 9
	v_readlane_b32 s86, v253, 10
	v_readlane_b32 s87, v253, 11
	v_readlane_b32 s88, v253, 12
	v_readlane_b32 s89, v253, 13
	s_waitcnt vmcnt(0)
	v_add_f32_e32 v2, v4, v2
	v_max_f32_e32 v4, 0, v2
	v_mul_f32_e64 v2, |v2|, s41
	v_exp_f32_e32 v5, v2
	s_mov_b32 s41, 0x3f2aaaab
	v_add_f32_e32 v8, 1.0, v5
	v_add_f32_e32 v2, -1.0, v8
	v_sub_f32_e32 v3, v2, v8
	v_add_f32_e32 v3, 1.0, v3
	v_sub_f32_e32 v2, v5, v2
	v_add_f32_e32 v9, v2, v3
	v_frexp_mant_f32_e32 v2, v8
	v_cmp_gt_f32_e32 vcc, s41, v2
	v_cvt_f64_f32_e32 v[2:3], v8
	v_frexp_exp_i32_f64_e32 v2, v[2:3]
	v_subbrev_co_u32_e32 v2, vcc, 0, v2, vcc
	v_sub_u32_e32 v3, 0, v2
	v_ldexp_f32 v8, v8, v3
	v_ldexp_f32 v3, v9, v3
	v_add_f32_e32 v9, -1.0, v8
	v_add_f32_e32 v10, 1.0, v9
	v_sub_f32_e32 v10, v8, v10
	v_add_f32_e32 v10, v3, v10
	v_add_f32_e32 v11, v9, v10
	v_sub_f32_e32 v9, v11, v9
	v_sub_f32_e32 v9, v10, v9
	v_add_f32_e32 v10, 1.0, v8
	v_add_f32_e32 v12, -1.0, v10
	v_sub_f32_e32 v8, v8, v12
	v_add_f32_e32 v3, v3, v8
	v_add_f32_e32 v8, v10, v3
	v_sub_f32_e32 v10, v8, v10
	v_sub_f32_e32 v3, v3, v10
	v_rcp_f32_e32 v10, v8
	v_cvt_f32_i32_e32 v2, v2
	s_mov_b32 s41, 0x3f317218
	v_mul_f32_e32 v12, v11, v10
	v_mul_f32_e32 v13, v8, v12
	v_fma_f32 v14, v12, v8, -v13
	v_fmac_f32_e32 v14, v12, v3
	v_add_f32_e32 v15, v13, v14
	v_sub_f32_e32 v16, v11, v15
	v_sub_f32_e32 v11, v11, v16
	v_sub_f32_e32 v13, v15, v13
	v_sub_f32_e32 v11, v11, v15
	v_add_f32_e32 v9, v9, v11
	v_sub_f32_e32 v11, v13, v14
	v_add_f32_e32 v9, v11, v9
	v_add_f32_e32 v11, v16, v9
	v_mul_f32_e32 v13, v10, v11
	v_mul_f32_e32 v14, v8, v13
	v_fma_f32 v8, v13, v8, -v14
	v_fmac_f32_e32 v8, v13, v3
	v_sub_f32_e32 v3, v16, v11
	v_add_f32_e32 v3, v9, v3
	v_add_f32_e32 v9, v14, v8
	v_sub_f32_e32 v15, v11, v9
	v_sub_f32_e32 v11, v11, v15
	v_sub_f32_e32 v14, v9, v14
	v_sub_f32_e32 v9, v11, v9
	v_add_f32_e32 v3, v3, v9
	v_sub_f32_e32 v8, v14, v8
	v_add_f32_e32 v3, v8, v3
	v_add_f32_e32 v8, v12, v13
	v_add_f32_e32 v3, v15, v3
	v_sub_f32_e32 v9, v8, v12
	v_mul_f32_e32 v3, v10, v3
	v_sub_f32_e32 v9, v13, v9
	v_add_f32_e32 v3, v9, v3
	v_mul_f32_e32 v12, 0x3f317218, v2
	v_add_f32_e32 v9, v8, v3
	v_fma_f32 v13, v2, s41, -v12
	v_mul_f32_e32 v10, v9, v9
	v_fmac_f32_e32 v13, 0xb102e308, v2
	v_sub_f32_e32 v2, v9, v8
	v_fmamk_f32 v11, v10, 0x3e9b6dac, v197
	v_sub_f32_e32 v2, v3, v2
	v_add_f32_e32 v3, v12, v13
	v_fmaak_f32 v11, v10, v11, 0x3f2aaada
	v_sub_f32_e32 v8, v3, v12
	v_ldexp_f32 v12, v9, 1
	v_mul_f32_e32 v9, v9, v10
	v_mul_f32_e32 v9, v9, v11
	v_add_f32_e32 v10, v12, v9
	v_sub_f32_e32 v11, v10, v12
	v_ldexp_f32 v2, v2, 1
	v_sub_f32_e32 v9, v9, v11
	v_add_f32_e32 v2, v2, v9
	v_add_f32_e32 v9, v10, v2
	v_sub_f32_e32 v10, v9, v10
	v_sub_f32_e32 v2, v2, v10
	v_add_f32_e32 v10, v3, v9
	v_sub_f32_e32 v11, v10, v3
	v_sub_f32_e32 v12, v10, v11
	v_sub_f32_e32 v8, v13, v8
	v_sub_f32_e32 v3, v3, v12
	v_sub_f32_e32 v9, v9, v11
	v_add_f32_e32 v3, v9, v3
	v_add_f32_e32 v9, v8, v2
	v_sub_f32_e32 v11, v9, v8
	v_sub_f32_e32 v12, v9, v11
	v_sub_f32_e32 v8, v8, v12
	v_sub_f32_e32 v2, v2, v11
	v_add_f32_e32 v3, v9, v3
	v_add_f32_e32 v2, v2, v8
	v_add_f32_e32 v8, v10, v3
	v_sub_f32_e32 v9, v8, v10
	v_sub_f32_e32 v3, v3, v9
	v_add_f32_e32 v2, v2, v3
	s_mov_b32 s41, 0x7f800000
	v_add_f32_e32 v2, v8, v2
	v_cmp_neq_f32_e32 vcc, s41, v5
	s_mov_b32 s41, 0x33800000
	s_nop 0
	v_cndmask_b32_e32 v2, v211, v2, vcc
	v_cmp_ngt_f32_e32 vcc, -1.0, v5
	s_nop 1
	v_cndmask_b32_e32 v2, v212, v2, vcc
	v_cmp_neq_f32_e32 vcc, -1.0, v5
	s_nop 1
	v_cndmask_b32_e32 v2, v213, v2, vcc
	v_cmp_lt_f32_e64 vcc, |v5|, s41
	s_nop 1
	v_cndmask_b32_e32 v2, v2, v5, vcc
	v_add_f32_e32 v2, v4, v2
	v_mov_b32_e32 v3, v250
	v_add_u32_e32 v5, -1, v198
	v_cmp_lt_i32_e32 vcc, v5, v227
	s_waitcnt vmcnt(0)
	v_mul_f32_e32 v3, 0x3fb8aa3b, v3
	v_exp_f32_e32 v3, v3
	v_cndmask_b32_e32 v5, v5, v198, vcc
	v_lshlrev_b32_e32 v5, 2, v5
	v_cmp_eq_u32_e32 vcc, 0, v0
	v_mul_f32_e64 v4, v2, -v3
	ds_bpermute_b32 v5, v5, v4
	s_waitcnt lgkmcnt(0)
	v_fma_f32 v3, v2, -v3, v5
	v_cndmask_b32_e32 v3, v3, v4, vcc
	v_add_u32_e32 v4, -2, v198
	v_cmp_lt_i32_e32 vcc, v4, v227
	s_nop 1
	v_cndmask_b32_e32 v4, v4, v198, vcc
	v_lshlrev_b32_e32 v4, 2, v4
	ds_bpermute_b32 v4, v4, v3
	v_cmp_gt_u32_e32 vcc, 2, v0
	s_waitcnt lgkmcnt(0)
; #define LAS __attribute__((address_space(3)))
; __device__ void phase_ssd3(const Params& p, bf16_t* ymix, LAS unsigned char* lds, int wg, int nwg) {
;     ...
;         const bf16_t* hb = S + ((((size_t)b * 128 + c) * 32 + eg) * 64) * 128;
;         bf16x8 hfa[4][4];
; #pragma unroll
;         for (int ks = 0; ks < 4; ++ks)
; #pragma unroll
;             for (int pt = 0; pt < 4; ++pt) hfa[ks][pt] = *(const bf16x8*)(hb + (size_t)(16 * pt + fr) * 128 + 32 * ks + 8 * fq);
;         LDS_BARRIER();
;         {
;             const int st = e >> 1;
;             f32x4 cbacc[2] = {(f32x4){0.f, 0.f, 0.f, 0.f}, (f32x4){0.f, 0.f, 0.f, 0.f}};
; #pragma unroll
;             for (int ks = 0; ks < 4; ++ks) {
;                 const bf16x8 bfr = *(LAS const bf16x8*)(lds + SSD_B + ((16 * st + fr) * 136 + 32 * ks + 8 * fq) * 2);
; #pragma unroll
;                 for (int j = 0; j < 2; ++j) { const int lt = 2 * (e & 1) + j; const bf16x8 cfr = *(LAS const bf16x8*)(lds + SSD_C + ((16 * lt + fr) * 136 + 32 * ks + 8 * fq) * 2); cbacc[j] = __builtin_amdgcn_mfma_f32_16x16x32_bf16(bfr, cfr, cbacc[j], 0, 0, 0); }
;             }
; #pragma unroll
;             for (int j = 0; j < 2; ++j) { const int lt = 2 * (e & 1) + j; *(LAS f32x4*)(lds + SSD_CB + ((16 * lt + fr) * 68 + 16 * st + 4 * fq) * 4) = cbacc[j]; }
;         }
;         LDS_BARRIER();
;         LAS const float* ACS = (LAS const float*)(lds + SSD_ACS); LAS const float* DT = (LAS const float*)(lds + SSD_DT);
;         const float Dsk = p.in[I_SSDD][eg];
;         f32x4 acc[4][4];
; #pragma unroll
;         for (int pt = 0; pt < 4; ++pt)
; #pragma unroll
;             for (int lt = 0; lt < 4; ++lt) acc[pt][lt] = (f32x4){0.f, 0.f, 0.f, 0.f};
; #pragma unroll
;         for (int ks = 0; ks < 4; ++ks) {
;             bf16x8 hf[4], cf[4];
; #pragma unroll
;             for (int pt = 0; pt < 4; ++pt) hf[pt] = hfa[ks][pt];
; #pragma unroll
;             for (int lt = 0; lt < 4; ++lt) cf[lt] = *(LAS const bf16x8*)(lds + SSD_C + ((16 * lt + fr) * 136 + 32 * ks + 8 * fq) * 2);
; #pragma unroll
;             for (int pt = 0; pt < 4; ++pt)
; #pragma unroll
;                 for (int lt = 0; lt < 4; ++lt) acc[pt][lt] = __builtin_amdgcn_mfma_f32_16x16x32_bf16(hf[pt], cf[lt], acc[pt][lt], 0, 0, 0);
;         }
	v_add_f32_e32 v4, v3, v4
	v_cndmask_b32_e32 v3, v4, v3, vcc
	v_add_u32_e32 v4, -4, v198
	v_cmp_lt_i32_e32 vcc, v4, v227
	s_nop 1
	v_cndmask_b32_e32 v4, v4, v198, vcc
	v_lshlrev_b32_e32 v4, 2, v4
	ds_bpermute_b32 v4, v4, v3
	v_cmp_gt_u32_e32 vcc, 4, v0
	s_waitcnt lgkmcnt(0)
	v_add_f32_e32 v4, v3, v4
	v_cndmask_b32_e32 v3, v4, v3, vcc
	v_add_u32_e32 v4, -8, v198
	v_cmp_lt_i32_e32 vcc, v4, v227
	s_nop 1
	v_cndmask_b32_e32 v4, v4, v198, vcc
	v_lshlrev_b32_e32 v4, 2, v4
	ds_bpermute_b32 v4, v4, v3
	v_cmp_gt_u32_e32 vcc, 8, v0
	s_waitcnt lgkmcnt(0)
	v_add_f32_e32 v4, v3, v4
	v_cndmask_b32_e32 v3, v4, v3, vcc
	v_add_u32_e32 v4, -16, v198
	v_cmp_lt_i32_e32 vcc, v4, v227
	s_nop 1
	v_cndmask_b32_e32 v4, v4, v198, vcc
	v_lshlrev_b32_e32 v4, 2, v4
	ds_bpermute_b32 v4, v4, v3
	v_cmp_gt_u32_e32 vcc, 16, v0
	s_waitcnt lgkmcnt(0)
	v_add_f32_e32 v4, v3, v4
	v_cndmask_b32_e32 v3, v4, v3, vcc
	v_subrev_u32_e32 v4, 32, v198
	v_cmp_lt_i32_e32 vcc, v4, v227
	s_nop 1
	v_cndmask_b32_e32 v4, v4, v198, vcc
	v_lshlrev_b32_e32 v4, 2, v4
	ds_bpermute_b32 v4, v4, v3
	v_cmp_gt_u32_e32 vcc, 32, v0
	v_lshl_add_u32 v0, v0, 3, v1
	v_lshl_add_u32 v0, v0, 2, 0
	v_add_u32_e32 v1, 0x1f000, v0
	s_waitcnt lgkmcnt(0)
	v_add_f32_e32 v4, v3, v4
	v_cndmask_b32_e32 v3, v4, v3, vcc
	v_add_u32_e32 v0, 0x1f800, v0
	ds_write_b32 v1, v3
	ds_write_b32 v0, v2
	v_lshl_add_u64 v[0:1], s[42:43], 0, v[68:69]
	v_lshlrev_b64 v[0:1], 14, v[0:1]
	v_lshl_add_u64 v[0:1], v[116:117], 0, v[0:1]
	v_lshl_add_u64 v[2:3], v[0:1], 0, v[114:115]
	v_lshl_add_u64 v[4:5], v[0:1], 0, v[128:129]
	global_load_dwordx4 v[52:55], v[4:5], off
	global_load_dwordx4 v[44:47], v[2:3], off offset:128
	v_lshl_add_u64 v[4:5], v[0:1], 0, v[130:131]
	global_load_dwordx4 v[56:59], v[4:5], off
	v_lshl_add_u64 v[4:5], v[0:1], 0, v[132:133]
	global_load_dwordx4 v[48:51], v[2:3], off
	global_load_dwordx4 v[28:31], v[2:3], off offset:64
	global_load_dwordx4 v[60:63], v[4:5], off
	v_lshl_add_u64 v[4:5], v[0:1], 0, 64
	v_lshl_add_u64 v[6:7], v[4:5], 0, v[128:129]
	global_load_dwordx4 v[24:27], v[6:7], off
	v_lshl_add_u64 v[6:7], v[4:5], 0, v[130:131]
	v_lshl_add_u64 v[4:5], v[4:5], 0, v[132:133]
	global_load_dwordx4 v[20:23], v[6:7], off
	global_load_dwordx4 v[16:19], v[4:5], off
	s_mov_b64 s[42:43], 0x80
	v_lshl_add_u64 v[4:5], v[0:1], 0, s[42:43]
	v_lshl_add_u64 v[6:7], v[4:5], 0, v[128:129]
	global_load_dwordx4 v[40:43], v[6:7], off
	v_lshl_add_u64 v[6:7], v[4:5], 0, v[130:131]
	global_load_dwordx4 v[36:39], v[6:7], off
	v_lshl_add_u64 v[4:5], v[4:5], 0, v[132:133]
	global_load_dwordx4 v[32:35], v[4:5], off
	s_mov_b64 s[42:43], 0xc0
	v_lshl_add_u64 v[12:13], v[0:1], 0, s[42:43]
	global_load_dwordx4 v[0:3], v[2:3], off offset:192
	v_lshl_add_u64 v[4:5], v[12:13], 0, v[128:129]
	v_lshl_add_u64 v[8:9], v[12:13], 0, v[130:131]
	v_lshl_add_u64 v[12:13], v[12:13], 0, v[132:133]
	global_load_dwordx4 v[8:11], v[8:9], off
	s_nop 0
	global_load_dwordx4 v[12:15], v[12:13], off
	s_nop 0
	global_load_dwordx4 v[4:7], v[4:5], off
	s_waitcnt lgkmcnt(0)
	s_barrier
	ds_read_b128 v[64:67], v199
	ds_read_b128 v[70:73], v214
	ds_read_b128 v[74:77], v215
	s_waitcnt lgkmcnt(1)
	v_mfma_f32_16x16x32_bf16 v[70:73], v[64:67], v[70:73], 0
	s_waitcnt lgkmcnt(0)
	v_mfma_f32_16x16x32_bf16 v[64:67], v[64:67], v[74:77], 0
	ds_read_b128 v[74:77], v199 offset:64
	ds_read_b128 v[78:81], v216
	s_waitcnt lgkmcnt(0)
	v_mfma_f32_16x16x32_bf16 v[70:73], v[74:77], v[78:81], v[70:73]
	ds_read_b128 v[78:81], v217
	s_waitcnt lgkmcnt(0)
	v_mfma_f32_16x16x32_bf16 v[64:67], v[74:77], v[78:81], v[64:67]
	ds_read_b128 v[74:77], v199 offset:128
	ds_read_b128 v[78:81], v218
	s_waitcnt lgkmcnt(0)
	v_mfma_f32_16x16x32_bf16 v[70:73], v[74:77], v[78:81], v[70:73]
	ds_read_b128 v[78:81], v219
	s_waitcnt lgkmcnt(0)
	v_mfma_f32_16x16x32_bf16 v[64:67], v[74:77], v[78:81], v[64:67]
	ds_read_b128 v[74:77], v199 offset:192
	ds_read_b128 v[78:81], v220
	s_waitcnt lgkmcnt(0)
	v_mfma_f32_16x16x32_bf16 v[70:73], v[74:77], v[78:81], v[70:73]
	ds_read_b128 v[78:81], v221
	s_waitcnt lgkmcnt(0)
	v_mfma_f32_16x16x32_bf16 v[64:67], v[74:77], v[78:81], v[64:67]
	s_nop 4
	ds_write_b128 v200, v[70:73]
	s_nop 1
	ds_write_b128 v200, v[64:67] offset:4352
	s_waitcnt lgkmcnt(0)
	s_barrier
	v_lshl_add_u64 v[64:65], v[68:69], 2, s[94:95]
	global_load_dword v129, v[64:65], off
	ds_read_b128 v[64:67], v201
	ds_read_b128 v[70:73], v201 offset:4352
	ds_read_b128 v[74:77], v201 offset:8704
	ds_read_b128 v[78:81], v201 offset:13056
	s_waitcnt vmcnt(13) lgkmcnt(3)
	v_mfma_f32_16x16x32_bf16 v[82:85], v[48:51], v[64:67], 0
	s_waitcnt lgkmcnt(2)
	v_mfma_f32_16x16x32_bf16 v[86:89], v[48:51], v[70:73], 0
	s_waitcnt lgkmcnt(1)
	v_mfma_f32_16x16x32_bf16 v[90:93], v[48:51], v[74:77], 0
	s_waitcnt lgkmcnt(0)
	v_mfma_f32_16x16x32_bf16 v[48:51], v[48:51], v[78:81], 0
	v_mfma_f32_16x16x32_bf16 v[94:97], v[52:55], v[64:67], 0
	v_mfma_f32_16x16x32_bf16 v[98:101], v[52:55], v[70:73], 0
	v_mfma_f32_16x16x32_bf16 v[102:105], v[52:55], v[74:77], 0
	v_mfma_f32_16x16x32_bf16 v[52:55], v[52:55], v[78:81], 0
	v_mfma_f32_16x16x32_bf16 v[106:109], v[56:59], v[64:67], 0
	v_mfma_f32_16x16x32_bf16 v[134:137], v[56:59], v[70:73], 0
	v_mfma_f32_16x16x32_bf16 v[138:141], v[56:59], v[74:77], 0
	v_mfma_f32_16x16x32_bf16 v[56:59], v[56:59], v[78:81], 0
	s_waitcnt vmcnt(11)
	v_mfma_f32_16x16x32_bf16 v[64:67], v[60:63], v[64:67], 0
	v_mfma_f32_16x16x32_bf16 v[70:73], v[60:63], v[70:73], 0
	v_mfma_f32_16x16x32_bf16 v[74:77], v[60:63], v[74:77], 0
	v_mfma_f32_16x16x32_bf16 v[60:63], v[60:63], v[78:81], 0
	ds_read_b128 v[78:81], v201 offset:64
	ds_read_b128 v[142:145], v201 offset:4416
	ds_read_b128 v[146:149], v201 offset:8768
	ds_read_b128 v[150:153], v201 offset:13120
	s_waitcnt lgkmcnt(3)
; #define LAS __attribute__((address_space(3)))
; __device__ void phase_ssd3(const Params& p, bf16_t* ymix, LAS unsigned char* lds, int wg, int nwg) {
;     ...
;         for (int ks = 0; ks < 4; ++ks) {
;             bf16x8 hf[4], cf[4];
; #pragma unroll
;             for (int pt = 0; pt < 4; ++pt) hf[pt] = hfa[ks][pt];
; #pragma unroll
;             for (int lt = 0; lt < 4; ++lt) cf[lt] = *(LAS const bf16x8*)(lds + SSD_C + ((16 * lt + fr) * 136 + 32 * ks + 8 * fq) * 2);
; #pragma unroll
;             for (int pt = 0; pt < 4; ++pt)
; #pragma unroll
;                 for (int lt = 0; lt < 4; ++lt) acc[pt][lt] = __builtin_amdgcn_mfma_f32_16x16x32_bf16(hf[pt], cf[lt], acc[pt][lt], 0, 0, 0);
;         }
;         u32x2 zr[4][4];
; #pragma unroll
;         for (int lt = 0; lt < 4; ++lt)
; #pragma unroll
;             for (int pt = 0; pt < 4; ++pt) zr[lt][pt] = *(const u32x2*)(Z + (m0 + 16 * lt + fr) * D_SSD + 64 * eg + 16 * pt + 4 * fq);
;         float acl[4];
; #pragma unroll
;         for (int lt = 0; lt < 4; ++lt) { acl[lt] = ACS[(16 * lt + fr) * 8 + e]; const float sc = __expf(acl[lt]);
	v_mfma_f32_16x16x32_bf16 v[82:85], v[28:31], v[78:81], v[82:85]
	s_waitcnt lgkmcnt(2)
	v_mfma_f32_16x16x32_bf16 v[86:89], v[28:31], v[142:145], v[86:89]
	s_waitcnt lgkmcnt(1)
	v_mfma_f32_16x16x32_bf16 v[90:93], v[28:31], v[146:149], v[90:93]
	s_waitcnt lgkmcnt(0)
	v_mfma_f32_16x16x32_bf16 v[28:31], v[28:31], v[150:153], v[48:51]
	s_waitcnt vmcnt(10)
	v_mfma_f32_16x16x32_bf16 v[48:51], v[24:27], v[78:81], v[94:97]
	v_mfma_f32_16x16x32_bf16 v[94:97], v[24:27], v[142:145], v[98:101]
	v_mfma_f32_16x16x32_bf16 v[98:101], v[24:27], v[146:149], v[102:105]
	v_mfma_f32_16x16x32_bf16 v[24:27], v[24:27], v[150:153], v[52:55]
	s_waitcnt vmcnt(9)
	v_mfma_f32_16x16x32_bf16 v[52:55], v[20:23], v[78:81], v[106:109]
	v_mfma_f32_16x16x32_bf16 v[102:105], v[20:23], v[142:145], v[134:137]
	v_mfma_f32_16x16x32_bf16 v[106:109], v[20:23], v[146:149], v[138:141]
	v_mfma_f32_16x16x32_bf16 v[20:23], v[20:23], v[150:153], v[56:59]
	s_waitcnt vmcnt(8)
	v_mfma_f32_16x16x32_bf16 v[56:59], v[16:19], v[78:81], v[64:67]
	v_mfma_f32_16x16x32_bf16 v[64:67], v[16:19], v[142:145], v[70:73]
	v_mfma_f32_16x16x32_bf16 v[70:73], v[16:19], v[146:149], v[74:77]
	v_mfma_f32_16x16x32_bf16 v[16:19], v[16:19], v[150:153], v[60:63]
	s_nop 2
	ds_read_b128 v[60:63], v201 offset:128
	ds_read_b128 v[74:77], v201 offset:4480
	ds_read_b128 v[78:81], v201 offset:8832
	ds_read_b128 v[134:137], v201 offset:13184
	s_waitcnt vmcnt(6) lgkmcnt(2)
	v_mfma_f32_16x16x32_bf16 v[102:105], v[36:39], v[74:77], v[102:105]
	s_waitcnt lgkmcnt(1)
	v_mfma_f32_16x16x32_bf16 v[90:93], v[44:47], v[78:81], v[90:93]
	s_waitcnt lgkmcnt(0)
	v_mfma_f32_16x16x32_bf16 v[28:31], v[44:47], v[134:137], v[28:31]
	v_mfma_f32_16x16x32_bf16 v[48:51], v[40:43], v[60:63], v[48:51]
	v_mfma_f32_16x16x32_bf16 v[94:97], v[40:43], v[74:77], v[94:97]
	v_mfma_f32_16x16x32_bf16 v[98:101], v[40:43], v[78:81], v[98:101]
	v_mfma_f32_16x16x32_bf16 v[40:43], v[40:43], v[134:137], v[24:27]
	v_mfma_f32_16x16x32_bf16 v[52:55], v[36:39], v[60:63], v[52:55]
	v_mfma_f32_16x16x32_bf16 v[106:109], v[36:39], v[78:81], v[106:109]
	v_mfma_f32_16x16x32_bf16 v[36:39], v[36:39], v[134:137], v[20:23]
	s_waitcnt vmcnt(5)
	v_mfma_f32_16x16x32_bf16 v[70:73], v[32:35], v[78:81], v[70:73]
	v_mfma_f32_16x16x32_bf16 v[78:81], v[32:35], v[134:137], v[16:19]
	ds_read_b128 v[134:137], v201 offset:192
	ds_read_b128 v[138:141], v201 offset:4544
	ds_read_b128 v[142:145], v201 offset:8896
	ds_read_b128 v[146:149], v201 offset:13248
	v_mfma_f32_16x16x32_bf16 v[82:85], v[44:47], v[60:63], v[82:85]
	v_mfma_f32_16x16x32_bf16 v[86:89], v[44:47], v[74:77], v[86:89]
	v_mfma_f32_16x16x32_bf16 v[56:59], v[32:35], v[60:63], v[56:59]
	v_mfma_f32_16x16x32_bf16 v[74:77], v[32:35], v[74:77], v[64:67]
	s_waitcnt vmcnt(3) lgkmcnt(2)
	v_mfma_f32_16x16x32_bf16 v[64:67], v[8:11], v[138:141], v[102:105]
	s_nop 2
	v_lshlrev_b32_e32 v104, 6, v68
	v_ashrrev_i32_e32 v105, 31, v104
	v_mov_b32_e32 v103, s61
	v_or_b32_e32 v102, s40, v112
	v_mfma_f32_16x16x32_bf16 v[44:47], v[0:3], v[134:137], v[82:85]
	v_mfma_f32_16x16x32_bf16 v[24:27], v[0:3], v[138:141], v[86:89]
	s_waitcnt lgkmcnt(1)
	v_mfma_f32_16x16x32_bf16 v[16:19], v[0:3], v[142:145], v[90:93]
	s_waitcnt lgkmcnt(0)
	v_mfma_f32_16x16x32_bf16 v[0:3], v[0:3], v[146:149], v[28:31]
	s_waitcnt vmcnt(1)
	v_mfma_f32_16x16x32_bf16 v[32:35], v[4:7], v[134:137], v[48:51]
	v_mfma_f32_16x16x32_bf16 v[60:63], v[4:7], v[138:141], v[94:97]
	v_mfma_f32_16x16x32_bf16 v[28:31], v[4:7], v[142:145], v[98:101]
	s_nop 1
	v_mov_b32_e32 v97, s61
	v_or_b32_e32 v96, s40, v124
	v_mfma_f32_16x16x32_bf16 v[4:7], v[4:7], v[146:149], v[40:43]
	v_mov_b32_e32 v101, s61
	v_or_b32_e32 v100, s40, v120
	v_mov_b32_e32 v99, s61
	v_mfma_f32_16x16x32_bf16 v[20:23], v[8:11], v[134:137], v[52:55]
	v_or_b32_e32 v98, s40, v122
	v_readlane_b32 s40, v253, 54
	v_readlane_b32 s41, v253, 55
	v_mfma_f32_16x16x32_bf16 v[52:55], v[8:11], v[142:145], v[106:109]
	v_mfma_f32_16x16x32_bf16 v[36:39], v[8:11], v[146:149], v[36:39]
	v_mfma_f32_16x16x32_bf16 v[40:43], v[12:15], v[134:137], v[56:59]
	v_mfma_f32_16x16x32_bf16 v[8:11], v[12:15], v[138:141], v[74:77]
	v_mfma_f32_16x16x32_bf16 v[56:59], v[12:15], v[142:145], v[70:73]
	v_mfma_f32_16x16x32_bf16 v[48:51], v[12:15], v[146:149], v[78:81]
	v_lshl_add_u64 v[12:13], v[104:105], 1, v[118:119]
	v_lshlrev_b64 v[14:15], 12, v[102:103]
	v_lshl_add_u64 v[14:15], v[12:13], 0, v[14:15]
	global_load_dwordx2 v[158:159], v[14:15], off
	global_load_dwordx2 v[156:157], v[14:15], off offset:32
	global_load_dwordx2 v[154:155], v[14:15], off offset:64
	global_load_dwordx2 v[152:153], v[14:15], off offset:96
	v_lshlrev_b64 v[14:15], 12, v[100:101]
	v_lshl_add_u64 v[14:15], v[12:13], 0, v[14:15]
	global_load_dwordx2 v[150:151], v[14:15], off
	global_load_dwordx2 v[148:149], v[14:15], off offset:32
	global_load_dwordx2 v[146:147], v[14:15], off offset:64
	global_load_dwordx2 v[144:145], v[14:15], off offset:96
	v_lshlrev_b64 v[14:15], 12, v[98:99]
	v_lshl_add_u64 v[14:15], v[12:13], 0, v[14:15]
	global_load_dwordx2 v[142:143], v[14:15], off
	global_load_dwordx2 v[140:141], v[14:15], off offset:32
	global_load_dwordx2 v[138:139], v[14:15], off offset:64
	global_load_dwordx2 v[136:137], v[14:15], off offset:96
	v_lshlrev_b64 v[14:15], 12, v[96:97]
	v_lshl_add_u64 v[12:13], v[12:13], 0, v[14:15]
	global_load_dwordx2 v[134:135], v[12:13], off
	global_load_dwordx2 v[110:111], v[12:13], off offset:32
	global_load_dwordx2 v[108:109], v[12:13], off offset:64
	global_load_dwordx2 v[106:107], v[12:13], off offset:96
	ds_read2st64_b32 v[84:85], v202 offset1:2
	ds_read2st64_b32 v[160:161], v202 offset0:4 offset1:6
	s_waitcnt lgkmcnt(1)
; #define LAS __attribute__((address_space(3)))
; __device__ void phase_ssd3(const Params& p, bf16_t* ymix, LAS unsigned char* lds, int wg, int nwg) {
;     ...
;         float acl[4];
; #pragma unroll
;         for (int lt = 0; lt < 4; ++lt) { acl[lt] = ACS[(16 * lt + fr) * 8 + e]; const float sc = __expf(acl[lt]);
; #pragma unroll
;             for (int pt = 0; pt < 4; ++pt) acc[pt][lt] = acc[pt][lt] * sc; }
; #pragma unroll
;         for (int ks = 0; ks < 2; ++ks) {
;             float as_[8], ds_[8];
; #pragma unroll
;             for (int j = 0; j < 8; ++j) { const int s = 32 * ks + 8 * fq + j; as_[j] = ACS[s * 8 + e]; ds_[j] = DT[s * 8 + e]; }
;             bf16x8 xa[4];
; #pragma unroll
;             for (int pt = 0; pt < 4; ++pt) xa[pt] = *(LAS const bf16x8*)(lds + SSD_XT + ((64 * e + 16 * pt + fr) * 72 + 32 * ks + 8 * fq) * 2);
; #pragma unroll
;             for (int lt = 0; lt < 4; ++lt) {
;                 if (32 * ks > 16 * lt + 15) continue;
;                 const int l = 16 * lt + fr;
;                 const f32x4 c0 = *(LAS const f32x4*)(lds + SSD_CB + (l * 68 + 32 * ks + 8 * fq) * 4), c1 = *(LAS const f32x4*)(lds + SSD_CB + (l * 68 + 32 * ks + 8 * fq + 4) * 4);
;                 float mv[8];
; #pragma unroll
;                 for (int j = 0; j < 8; ++j) { const int s = 32 * ks + 8 * fq + j; const float cbv = j < 4 ? c0[j] : c1[j - 4];
;                     float v = cbv * __expf(fminf(acl[lt] - as_[j], 0.f)) * ds_[j]; v = (s <= l) ? v : 0.f; mv[j] = (s == l) ? v + Dsk : v; }
	v_mul_f32_e32 v12, 0x3fb8aa3b, v84
	v_exp_f32_e32 v12, v12
	s_nop 0
	v_pk_mul_f32 v[46:47], v[46:47], v[12:13] op_sel_hi:[1,0]
	v_pk_mul_f32 v[44:45], v[44:45], v[12:13] op_sel_hi:[1,0]
	v_pk_mul_f32 v[34:35], v[34:35], v[12:13] op_sel_hi:[1,0]
	v_pk_mul_f32 v[32:33], v[32:33], v[12:13] op_sel_hi:[1,0]
	v_pk_mul_f32 v[22:23], v[22:23], v[12:13] op_sel_hi:[1,0]
	v_pk_mul_f32 v[20:21], v[20:21], v[12:13] op_sel_hi:[1,0]
	v_pk_mul_f32 v[82:83], v[42:43], v[12:13] op_sel_hi:[1,0]
	v_pk_mul_f32 v[80:81], v[40:41], v[12:13] op_sel_hi:[1,0]
	v_mul_f32_e32 v12, 0x3fb8aa3b, v85
	v_exp_f32_e32 v68, v12
	s_nop 0
	v_pk_mul_f32 v[40:41], v[24:25], v[68:69] op_sel_hi:[1,0]
	v_pk_mul_f32 v[24:25], v[60:61], v[68:69] op_sel_hi:[1,0]
	s_waitcnt lgkmcnt(0)
	v_mul_f32_e32 v60, 0x3fb8aa3b, v160
	v_exp_f32_e32 v60, v60
	v_pk_mul_f32 v[42:43], v[26:27], v[68:69] op_sel_hi:[1,0]
	v_pk_mul_f32 v[26:27], v[62:63], v[68:69] op_sel_hi:[1,0]
	v_pk_mul_f32 v[14:15], v[66:67], v[68:69] op_sel_hi:[1,0]
	v_pk_mul_f32 v[76:77], v[16:17], v[60:61] op_sel_hi:[1,0]
	v_mul_f32_e32 v16, 0x3fb8aa3b, v161
	v_pk_mul_f32 v[12:13], v[64:65], v[68:69] op_sel_hi:[1,0]
	v_pk_mul_f32 v[10:11], v[10:11], v[68:69] op_sel_hi:[1,0]
	v_pk_mul_f32 v[8:9], v[8:9], v[68:69] op_sel_hi:[1,0]
	v_pk_mul_f32 v[68:69], v[52:53], v[60:61] op_sel_hi:[1,0]
	v_exp_f32_e32 v52, v16
	v_pk_mul_f32 v[78:79], v[18:19], v[60:61] op_sel_hi:[1,0]
	v_pk_mul_f32 v[74:75], v[30:31], v[60:61] op_sel_hi:[1,0]
	v_pk_mul_f32 v[72:73], v[28:29], v[60:61] op_sel_hi:[1,0]
	v_pk_mul_f32 v[70:71], v[54:55], v[60:61] op_sel_hi:[1,0]
	v_pk_mul_f32 v[62:63], v[58:59], v[60:61] op_sel_hi:[1,0]
	v_pk_mul_f32 v[60:61], v[56:57], v[60:61] op_sel_hi:[1,0]
	v_pk_mul_f32 v[30:31], v[2:3], v[52:53] op_sel_hi:[1,0]
	v_pk_mul_f32 v[28:29], v[0:1], v[52:53] op_sel_hi:[1,0]
	v_pk_mul_f32 v[18:19], v[6:7], v[52:53] op_sel_hi:[1,0]
	v_pk_mul_f32 v[16:17], v[4:5], v[52:53] op_sel_hi:[1,0]
	v_pk_mul_f32 v[6:7], v[38:39], v[52:53] op_sel_hi:[1,0]
	v_pk_mul_f32 v[4:5], v[36:37], v[52:53] op_sel_hi:[1,0]
	v_pk_mul_f32 v[2:3], v[50:51], v[52:53] op_sel_hi:[1,0]
	v_pk_mul_f32 v[0:1], v[48:49], v[52:53] op_sel_hi:[1,0]
	ds_read_b32 v231, v162
	ds_read_b32 v230, v163
	ds_read_b32 v229, v164
	ds_read_b32 v228, v165
	ds_read_b32 v133, v166
	ds_read_b32 v131, v167
	ds_read_b32 v95, v168
	ds_read_b32 v94, v169
	ds_read_b32 v93, v170
	ds_read_b32 v92, v171
	ds_read_b32 v91, v172
	ds_read_b32 v90, v173
	ds_read_b32 v89, v174
	ds_read_b32 v88, v175
	ds_read_b32 v87, v176
	ds_read_b32 v86, v177
	ds_read_b128 v[64:67], v203
	ds_read_b128 v[56:59], v203 offset:2304
	ds_read_b128 v[48:51], v203 offset:4608
	ds_read_b128 v[36:39], v203 offset:6912
	s_waitcnt lgkmcnt(14)
	v_sub_f32_e32 v195, v84, v231
	v_min_f32_e32 v195, 0, v195
	v_add_u32_e32 v52, s49, v178
	v_mul_f32_e32 v195, 0x3fb8aa3b, v195
	ds_read_b128 v[232:235], v52
	ds_read_b128 v[52:55], v52 offset:16
	v_exp_f32_e32 v195, v195
	s_waitcnt lgkmcnt(1)
	v_mul_f32_e32 v195, v195, v232
	v_mul_f32_e32 v195, v230, v195
	v_cndmask_b32_e64 v195, v195, 0, s[4:5]
	s_waitcnt vmcnt(16)
	v_add_f32_e32 v206, v129, v195
	v_cndmask_b32_e64 v195, v195, v206, s[6:7]
	v_sub_f32_e32 v206, v84, v229
	v_min_f32_e32 v206, 0, v206
	v_mul_f32_e32 v206, 0x3fb8aa3b, v206
	v_exp_f32_e32 v206, v206
	s_nop 0
	v_mul_f32_e32 v206, v206, v233
	v_mul_f32_e32 v206, v228, v206
	v_cndmask_b32_e64 v206, 0, v206, s[40:41]
	v_readlane_b32 s40, v254, 40
	v_add_f32_e32 v207, v129, v206
	v_readlane_b32 s41, v254, 41
	s_nop 1
	v_cndmask_b32_e64 v206, v206, v207, s[40:41]
	v_sub_f32_e32 v207, v84, v133
	v_min_f32_e32 v207, 0, v207
	v_mul_f32_e32 v207, 0x3fb8aa3b, v207
	v_exp_f32_e32 v207, v207
	v_readlane_b32 s40, v254, 4
	v_readlane_b32 s41, v254, 5
	v_mul_f32_e32 v207, v207, v234
	v_mul_f32_e32 v207, v131, v207
	v_cndmask_b32_e64 v207, v207, 0, s[40:41]
	v_readlane_b32 s40, v254, 6
	v_add_f32_e32 v208, v129, v207
	v_readlane_b32 s41, v254, 7
	s_nop 1
	v_cndmask_b32_e64 v207, v207, v208, s[40:41]
	v_sub_f32_e32 v208, v84, v95
	v_min_f32_e32 v208, 0, v208
	v_mul_f32_e32 v208, 0x3fb8aa3b, v208
	v_exp_f32_e32 v208, v208
	v_readlane_b32 s40, v254, 10
	v_readlane_b32 s41, v254, 11
	v_mul_f32_e32 v208, v208, v235
	v_mul_f32_e32 v208, v94, v208
	v_cndmask_b32_e64 v208, v208, 0, s[40:41]
	v_readlane_b32 s40, v254, 20
	v_add_f32_e32 v232, v129, v208
	v_readlane_b32 s41, v254, 21
	s_nop 1
	v_cndmask_b32_e64 v208, v208, v232, s[40:41]
	v_sub_f32_e32 v232, v84, v93
	v_min_f32_e32 v232, 0, v232
	v_mul_f32_e32 v232, 0x3fb8aa3b, v232
	v_exp_f32_e32 v232, v232
	v_readlane_b32 s40, v254, 22
	v_readlane_b32 s41, v254, 23
	s_waitcnt lgkmcnt(0)
; #define LAS __attribute__((address_space(3)))
; __device__ __forceinline__ unsigned cvt_pk_bf16(float lo, float hi) { unsigned r; asm volatile("v_cvt_pk_bf16_f32 %0, %1, %2" : "=v"(r) : "v"(lo), "v"(hi)); return r; }
; __device__ void phase_ssd3(const Params& p, bf16_t* ymix, LAS unsigned char* lds, int wg, int nwg) {
;     ...
;             for (int lt = 0; lt < 4; ++lt) {
;                 if (32 * ks > 16 * lt + 15) continue;
;                 const int l = 16 * lt + fr;
;                 const f32x4 c0 = *(LAS const f32x4*)(lds + SSD_CB + (l * 68 + 32 * ks + 8 * fq) * 4), c1 = *(LAS const f32x4*)(lds + SSD_CB + (l * 68 + 32 * ks + 8 * fq + 4) * 4);
;                 float mv[8];
; #pragma unroll
;                 for (int j = 0; j < 8; ++j) { const int s = 32 * ks + 8 * fq + j; const float cbv = j < 4 ? c0[j] : c1[j - 4];
;                     float v = cbv * __expf(fminf(acl[lt] - as_[j], 0.f)) * ds_[j]; v = (s <= l) ? v : 0.f; mv[j] = (s == l) ? v + Dsk : v; }
;                 u32x4 w; w.x = pg8::cvt_pk_bf16(mv[0], mv[1]); w.y = pg8::cvt_pk_bf16(mv[2], mv[3]); w.z = pg8::cvt_pk_bf16(mv[4], mv[5]); w.w = pg8::cvt_pk_bf16(mv[6], mv[7]);
;                 const bf16x8 mf = __builtin_bit_cast(bf16x8, w);
; #pragma unroll
;                 for (int pt = 0; pt < 4; ++pt) acc[pt][lt] = __builtin_amdgcn_mfma_f32_16x16x32_bf16(xa[pt], mf, acc[pt][lt], 0, 0, 0);
	v_mul_f32_e32 v52, v232, v52
	v_mul_f32_e32 v52, v92, v52
	v_cndmask_b32_e64 v52, v52, 0, s[40:41]
	v_readlane_b32 s40, v254, 24
	v_add_f32_e32 v232, v129, v52
	v_readlane_b32 s41, v254, 25
	s_nop 1
	v_cndmask_b32_e64 v52, v52, v232, s[40:41]
	v_sub_f32_e32 v232, v84, v91
	v_min_f32_e32 v232, 0, v232
	v_mul_f32_e32 v232, 0x3fb8aa3b, v232
	v_exp_f32_e32 v232, v232
	v_readlane_b32 s40, v254, 26
	v_readlane_b32 s41, v254, 27
	v_mul_f32_e32 v53, v232, v53
	v_mul_f32_e32 v53, v90, v53
	v_cndmask_b32_e64 v53, v53, 0, s[40:41]
	v_readlane_b32 s40, v254, 28
	v_add_f32_e32 v232, v129, v53
	v_readlane_b32 s41, v254, 29
	s_nop 1
	v_cndmask_b32_e64 v53, v53, v232, s[40:41]
	v_sub_f32_e32 v232, v84, v89
	v_min_f32_e32 v232, 0, v232
	v_mul_f32_e32 v232, 0x3fb8aa3b, v232
	v_exp_f32_e32 v232, v232
	v_sub_f32_e32 v84, v84, v87
	v_min_f32_e32 v84, 0, v84
	v_mul_f32_e32 v84, 0x3fb8aa3b, v84
	v_mul_f32_e32 v54, v232, v54
	v_readlane_b32 s40, v254, 30
	v_exp_f32_e32 v84, v84
	v_mul_f32_e32 v54, v88, v54
	v_readlane_b32 s41, v254, 31
	v_mul_f32_e32 v55, v84, v55
	s_nop 0
	v_cndmask_b32_e64 v54, v54, 0, s[40:41]
	v_readlane_b32 s40, v254, 32
	v_add_f32_e32 v232, v129, v54
	v_readlane_b32 s41, v254, 33
	v_mul_f32_e32 v55, v86, v55
	s_nop 0
	v_cndmask_b32_e64 v54, v54, v232, s[40:41]
	v_readlane_b32 s40, v254, 34
	v_readlane_b32 s41, v254, 35
	v_cvt_pk_bf16_f32 v232, v195, v206
	v_cvt_pk_bf16_f32 v233, v207, v208
	v_cvt_pk_bf16_f32 v234, v52, v53
	s_nop 1
	v_cndmask_b32_e64 v55, v55, 0, s[40:41]
	v_readlane_b32 s40, v254, 12
	v_add_f32_e32 v84, v129, v55
	v_readlane_b32 s41, v254, 13
	s_nop 1
	v_cndmask_b32_e64 v55, v55, v84, s[40:41]
	v_sub_f32_e32 v84, v85, v231
	v_min_f32_e32 v84, 0, v84
	v_cvt_pk_bf16_f32 v235, v54, v55
	v_mul_f32_e32 v84, 0x3fb8aa3b, v84
	v_mfma_f32_16x16x32_bf16 v[52:55], v[64:67], v[232:235], v[44:47]
	v_exp_f32_e32 v84, v84
	v_readlane_b32 s40, v254, 36
	v_readlane_b32 s41, v254, 37
	v_mfma_f32_16x16x32_bf16 v[44:47], v[56:59], v[232:235], v[32:35]
	v_mfma_f32_16x16x32_bf16 v[32:35], v[48:51], v[232:235], v[20:23]
	v_mfma_f32_16x16x32_bf16 v[20:23], v[36:39], v[232:235], v[80:83]
	ds_read_b128 v[232:235], v222
	s_nop 1
	ds_read_b128 v[80:83], v222 offset:16
	s_waitcnt lgkmcnt(1)
	v_mul_f32_e32 v84, v84, v232
	v_mul_f32_e32 v84, v230, v84
	v_cndmask_b32_e64 v84, v84, 0, s[40:41]
	v_readlane_b32 s40, v254, 38
	v_add_f32_e32 v195, v129, v84
	v_readlane_b32 s41, v254, 39
	s_nop 1
	v_cndmask_b32_e64 v84, v84, v195, s[40:41]
	v_sub_f32_e32 v195, v85, v229
	v_min_f32_e32 v195, 0, v195
	v_mul_f32_e32 v195, 0x3fb8aa3b, v195
	v_exp_f32_e32 v195, v195
	v_readlane_b32 s40, v253, 62
	v_readlane_b32 s41, v253, 63
	v_mul_f32_e32 v195, v195, v233
	v_mul_f32_e32 v195, v228, v195
	v_cndmask_b32_e64 v195, 0, v195, s[40:41]
	v_readlane_b32 s40, v254, 0
	v_add_f32_e32 v206, v129, v195
	v_readlane_b32 s41, v254, 1
	s_nop 1
	v_cndmask_b32_e64 v195, v195, v206, s[40:41]
	v_sub_f32_e32 v206, v85, v133
	v_min_f32_e32 v206, 0, v206
	v_mul_f32_e32 v206, 0x3fb8aa3b, v206
	v_exp_f32_e32 v206, v206
	v_readlane_b32 s40, v254, 2
	v_readlane_b32 s41, v254, 3
	v_mul_f32_e32 v206, v206, v234
	v_mul_f32_e32 v206, v131, v206
	v_cndmask_b32_e64 v206, v206, 0, s[40:41]
	v_readlane_b32 s40, v253, 47
	v_add_f32_e32 v207, v129, v206
	v_readlane_b32 s41, v253, 48
	s_nop 1
	v_cndmask_b32_e64 v206, v206, v207, s[40:41]
	v_sub_f32_e32 v207, v85, v95
	v_min_f32_e32 v207, 0, v207
	v_mul_f32_e32 v207, 0x3fb8aa3b, v207
	v_exp_f32_e32 v207, v207
	v_readlane_b32 s40, v254, 8
	v_readlane_b32 s41, v254, 9
	v_mul_f32_e32 v207, v207, v235
	v_mul_f32_e32 v207, v94, v207
	v_cndmask_b32_e64 v207, v207, 0, s[40:41]
	v_readlane_b32 s40, v254, 18
	v_add_f32_e32 v208, v129, v207
	v_readlane_b32 s41, v254, 19
	s_nop 1
	v_cndmask_b32_e64 v207, v207, v208, s[40:41]
	v_sub_f32_e32 v208, v85, v93
	v_min_f32_e32 v208, 0, v208
	v_mul_f32_e32 v208, 0x3fb8aa3b, v208
	v_exp_f32_e32 v208, v208
	v_readlane_b32 s40, v254, 44
	v_readlane_b32 s41, v254, 45
	s_waitcnt lgkmcnt(0)
	v_mul_f32_e32 v80, v208, v80
	v_mul_f32_e32 v80, v92, v80
	v_cndmask_b32_e64 v80, v80, 0, s[40:41]
	v_readlane_b32 s40, v254, 46
	v_add_f32_e32 v208, v129, v80
	v_readlane_b32 s41, v254, 47
	s_nop 1
	v_cndmask_b32_e64 v208, v80, v208, s[40:41]
	v_sub_f32_e32 v80, v85, v91
	v_min_f32_e32 v80, 0, v80
	v_mul_f32_e32 v80, 0x3fb8aa3b, v80
	v_exp_f32_e32 v80, v80
	v_readlane_b32 s40, v254, 42
	v_readlane_b32 s41, v254, 43
	v_mul_f32_e32 v80, v80, v81
	v_mul_f32_e32 v80, v90, v80
	v_cndmask_b32_e64 v80, v80, 0, s[40:41]
	v_readlane_b32 s40, v254, 14
	v_add_f32_e32 v81, v129, v80
	v_readlane_b32 s41, v254, 15
	s_nop 1
	v_cndmask_b32_e64 v232, v80, v81, s[40:41]
	v_sub_f32_e32 v80, v85, v89
	v_min_f32_e32 v80, 0, v80
	v_mul_f32_e32 v80, 0x3fb8aa3b, v80
	v_exp_f32_e32 v80, v80
	v_readlane_b32 s40, v254, 16
	v_readlane_b32 s41, v254, 17
	v_mul_f32_e32 v80, v80, v82
	v_mul_f32_e32 v80, v88, v80
	v_cndmask_b32_e64 v80, v80, 0, s[40:41]
	v_readlane_b32 s40, v253, 56
	v_add_f32_e32 v81, v129, v80
	v_readlane_b32 s41, v253, 57
	s_nop 1
	v_cndmask_b32_e64 v233, v80, v81, s[40:41]
	v_sub_f32_e32 v80, v85, v87
	v_min_f32_e32 v80, 0, v80
	v_mul_f32_e32 v80, 0x3fb8aa3b, v80
	v_exp_f32_e32 v80, v80
	v_readlane_b32 s40, v254, 48
	v_readlane_b32 s41, v254, 49
	v_sub_f32_e32 v85, v160, v91
	v_mul_f32_e32 v80, v80, v83
	v_mul_f32_e32 v80, v86, v80
	v_cndmask_b32_e64 v80, v80, 0, s[40:41]
	v_readlane_b32 s40, v254, 50
	v_add_f32_e32 v81, v129, v80
	v_readlane_b32 s41, v254, 51
	v_min_f32_e32 v85, 0, v85
	v_mul_f32_e32 v85, 0x3fb8aa3b, v85
	v_cndmask_b32_e64 v83, v80, v81, s[40:41]
	v_cvt_pk_bf16_f32 v80, v84, v195
	v_sub_f32_e32 v84, v160, v231
	v_min_f32_e32 v84, 0, v84
	v_cvt_pk_bf16_f32 v81, v206, v207
	v_cvt_pk_bf16_f32 v82, v208, v232
	v_cvt_pk_bf16_f32 v83, v233, v83
	v_mul_f32_e32 v84, 0x3fb8aa3b, v84
	v_mfma_f32_16x16x32_bf16 v[40:43], v[64:67], v[80:83], v[40:43]
	v_exp_f32_e32 v84, v84
	v_sub_f32_e32 v195, v160, v89
	v_sub_f32_e32 v206, v160, v87
	v_mfma_f32_16x16x32_bf16 v[24:27], v[56:59], v[80:83], v[24:27]
	v_exp_f32_e32 v85, v85
	v_min_f32_e32 v195, 0, v195
	v_min_f32_e32 v206, 0, v206
	v_mfma_f32_16x16x32_bf16 v[12:15], v[48:51], v[80:83], v[12:15]
	v_mul_f32_e32 v195, 0x3fb8aa3b, v195
	v_mul_f32_e32 v206, 0x3fb8aa3b, v206
	v_exp_f32_e32 v195, v195
	v_mfma_f32_16x16x32_bf16 v[8:11], v[36:39], v[80:83], v[8:11]
	ds_read_b128 v[80:83], v223
	ds_read_b128 v[232:235], v223 offset:16
	v_exp_f32_e32 v206, v206
	v_sub_f32_e32 v89, v161, v89
	v_sub_f32_e32 v87, v161, v87
	s_waitcnt lgkmcnt(1)
; #define LAS __attribute__((address_space(3)))
; __device__ __forceinline__ unsigned cvt_pk_bf16(float lo, float hi) { unsigned r; asm volatile("v_cvt_pk_bf16_f32 %0, %1, %2" : "=v"(r) : "v"(lo), "v"(hi)); return r; }
; __device__ void phase_ssd3(const Params& p, bf16_t* ymix, LAS unsigned char* lds, int wg, int nwg) {
;     ...
;         for (int ks = 0; ks < 2; ++ks) {
;             float as_[8], ds_[8];
; #pragma unroll
;             for (int j = 0; j < 8; ++j) { const int s = 32 * ks + 8 * fq + j; as_[j] = ACS[s * 8 + e]; ds_[j] = DT[s * 8 + e]; }
;             bf16x8 xa[4];
; #pragma unroll
;             for (int pt = 0; pt < 4; ++pt) xa[pt] = *(LAS const bf16x8*)(lds + SSD_XT + ((64 * e + 16 * pt + fr) * 72 + 32 * ks + 8 * fq) * 2);
; #pragma unroll
;             for (int lt = 0; lt < 4; ++lt) {
;                 if (32 * ks > 16 * lt + 15) continue;
;                 const int l = 16 * lt + fr;
;                 const f32x4 c0 = *(LAS const f32x4*)(lds + SSD_CB + (l * 68 + 32 * ks + 8 * fq) * 4), c1 = *(LAS const f32x4*)(lds + SSD_CB + (l * 68 + 32 * ks + 8 * fq + 4) * 4);
;                 float mv[8];
; #pragma unroll
;                 for (int j = 0; j < 8; ++j) { const int s = 32 * ks + 8 * fq + j; const float cbv = j < 4 ? c0[j] : c1[j - 4];
;                     float v = cbv * __expf(fminf(acl[lt] - as_[j], 0.f)) * ds_[j]; v = (s <= l) ? v : 0.f; mv[j] = (s == l) ? v + Dsk : v; }
;                 u32x4 w; w.x = pg8::cvt_pk_bf16(mv[0], mv[1]); w.y = pg8::cvt_pk_bf16(mv[2], mv[3]); w.z = pg8::cvt_pk_bf16(mv[4], mv[5]); w.w = pg8::cvt_pk_bf16(mv[6], mv[7]);
;                 const bf16x8 mf = __builtin_bit_cast(bf16x8, w);
; #pragma unroll
;                 for (int pt = 0; pt < 4; ++pt) acc[pt][lt] = __builtin_amdgcn_mfma_f32_16x16x32_bf16(xa[pt], mf, acc[pt][lt], 0, 0, 0);
	v_mul_f32_e32 v80, v84, v80
	v_sub_f32_e32 v84, v160, v229
	v_min_f32_e32 v84, 0, v84
	v_mul_f32_e32 v84, 0x3fb8aa3b, v84
	v_exp_f32_e32 v84, v84
	v_mul_f32_e32 v80, v230, v80
	s_waitcnt lgkmcnt(0)
	v_mul_f32_e32 v85, v85, v233
	v_mul_f32_e32 v85, v90, v85
	v_mul_f32_e32 v81, v84, v81
	v_sub_f32_e32 v84, v160, v133
	v_min_f32_e32 v84, 0, v84
	v_mul_f32_e32 v84, 0x3fb8aa3b, v84
	v_exp_f32_e32 v84, v84
	v_mul_f32_e32 v81, v228, v81
	v_cvt_pk_bf16_f32 v80, v80, v81
	v_mul_f32_e32 v195, v195, v234
	v_mul_f32_e32 v82, v84, v82
	v_sub_f32_e32 v84, v160, v95
	v_min_f32_e32 v84, 0, v84
	v_mul_f32_e32 v84, 0x3fb8aa3b, v84
	v_exp_f32_e32 v84, v84
	v_mul_f32_e32 v82, v131, v82
	v_mul_f32_e32 v206, v206, v235
	v_mul_f32_e32 v195, v88, v195
	v_mul_f32_e32 v83, v84, v83
	v_sub_f32_e32 v84, v160, v93
	v_min_f32_e32 v84, 0, v84
	v_mul_f32_e32 v84, 0x3fb8aa3b, v84
	v_exp_f32_e32 v84, v84
	v_mul_f32_e32 v83, v94, v83
	v_cvt_pk_bf16_f32 v81, v82, v83
	v_mul_f32_e32 v206, v86, v206
	v_mul_f32_e32 v84, v84, v232
	v_mul_f32_e32 v84, v92, v84
	v_cvt_pk_bf16_f32 v82, v84, v85
	v_sub_f32_e32 v84, v161, v231
	v_min_f32_e32 v84, 0, v84
	v_cvt_pk_bf16_f32 v83, v195, v206
	v_mul_f32_e32 v84, 0x3fb8aa3b, v84
	v_mfma_f32_16x16x32_bf16 v[76:79], v[64:67], v[80:83], v[76:79]
	v_exp_f32_e32 v84, v84
	v_sub_f32_e32 v85, v161, v91
	v_min_f32_e32 v85, 0, v85
	v_mfma_f32_16x16x32_bf16 v[72:75], v[56:59], v[80:83], v[72:75]
	v_min_f32_e32 v89, 0, v89
	v_min_f32_e32 v87, 0, v87
	v_mul_f32_e32 v85, 0x3fb8aa3b, v85
	v_mfma_f32_16x16x32_bf16 v[68:71], v[48:51], v[80:83], v[68:71]
	v_mul_f32_e32 v89, 0x3fb8aa3b, v89
	v_mul_f32_e32 v87, 0x3fb8aa3b, v87
	v_exp_f32_e32 v85, v85
	v_mfma_f32_16x16x32_bf16 v[80:83], v[36:39], v[80:83], v[60:63]
	s_nop 2
	ds_read_b128 v[60:63], v224
	ds_read_b128 v[232:235], v224 offset:16
	v_exp_f32_e32 v89, v89
	v_exp_f32_e32 v87, v87
	v_readlane_b32 s40, v254, 52
	s_waitcnt lgkmcnt(1)
	v_mul_f32_e32 v60, v84, v60
	v_sub_f32_e32 v84, v161, v229
	v_min_f32_e32 v84, 0, v84
	v_mul_f32_e32 v84, 0x3fb8aa3b, v84
	v_exp_f32_e32 v84, v84
	s_waitcnt lgkmcnt(0)
	v_mul_f32_e32 v85, v85, v233
	v_mul_f32_e32 v89, v89, v234
	v_mul_f32_e32 v87, v87, v235
	v_mul_f32_e32 v61, v84, v61
	v_sub_f32_e32 v84, v161, v133
	v_min_f32_e32 v84, 0, v84
	v_mul_f32_e32 v84, 0x3fb8aa3b, v84
	v_exp_f32_e32 v84, v84
	v_mul_f32_e32 v60, v230, v60
	v_mul_f32_e32 v61, v228, v61
	v_mul_f32_e32 v85, v90, v85
	v_mul_f32_e32 v62, v84, v62
	v_sub_f32_e32 v84, v161, v95
	v_min_f32_e32 v84, 0, v84
	v_mul_f32_e32 v84, 0x3fb8aa3b, v84
	v_exp_f32_e32 v84, v84
	v_mul_f32_e32 v62, v131, v62
	v_mul_f32_e32 v88, v88, v89
	v_mul_f32_e32 v86, v86, v87
	v_mul_f32_e32 v63, v84, v63
	v_sub_f32_e32 v84, v161, v93
	v_min_f32_e32 v84, 0, v84
	v_mul_f32_e32 v84, 0x3fb8aa3b, v84
	v_exp_f32_e32 v84, v84
	v_mul_f32_e32 v63, v94, v63
	v_cvt_pk_bf16_f32 v60, v60, v61
	v_cvt_pk_bf16_f32 v61, v62, v63
	v_mul_f32_e32 v84, v84, v232
	v_mul_f32_e32 v84, v92, v84
	v_cvt_pk_bf16_f32 v62, v84, v85
	v_cvt_pk_bf16_f32 v63, v88, v86
	v_readlane_b32 s41, v254, 53
	v_mfma_f32_16x16x32_bf16 v[28:31], v[64:67], v[60:63], v[28:31]
	v_mfma_f32_16x16x32_bf16 v[16:19], v[56:59], v[60:63], v[16:19]
	v_mfma_f32_16x16x32_bf16 v[4:7], v[48:51], v[60:63], v[4:7]
	v_mfma_f32_16x16x32_bf16 v[0:3], v[36:39], v[60:63], v[0:3]
	ds_read_b32 v131, v179
	ds_read_b32 v133, v180
	ds_read_b32 v195, v181
	ds_read_b32 v206, v182
	ds_read_b32 v207, v183
	ds_read_b32 v208, v184
	ds_read_b32 v228, v185
	ds_read_b32 v229, v186
	ds_read_b32 v230, v187
	ds_read_b32 v231, v188
	ds_read_b32 v232, v189
	ds_read_b32 v233, v190
	ds_read_b32 v234, v191
	ds_read_b32 v235, v192
	ds_read_b32 v236, v193
	ds_read_b32 v237, v196
	ds_read_b128 v[64:67], v203 offset:64
	ds_read_b128 v[84:87], v203 offset:2368
	ds_read_b128 v[88:91], v203 offset:4672
	ds_read_b128 v[92:95], v203 offset:6976
	ds_read_b128 v[48:51], v225
	ds_read_b128 v[36:39], v225 offset:16
	s_waitcnt lgkmcnt(14)
	v_sub_f32_e32 v56, v160, v131
	v_min_f32_e32 v56, 0, v56
	v_mul_f32_e32 v56, 0x3fb8aa3b, v56
	v_exp_f32_e32 v56, v56
	s_waitcnt lgkmcnt(1)
	v_mul_f32_e32 v48, v56, v48
	v_mul_f32_e32 v48, v133, v48
	v_cndmask_b32_e64 v48, v48, 0, s[4:5]
	v_add_f32_e32 v56, v129, v48
	v_cndmask_b32_e64 v48, v48, v56, s[6:7]
	v_sub_f32_e32 v56, v160, v195
	v_min_f32_e32 v56, 0, v56
	v_mul_f32_e32 v56, 0x3fb8aa3b, v56
	v_exp_f32_e32 v56, v56
	s_nop 0
	v_mul_f32_e32 v49, v56, v49
	v_mul_f32_e32 v49, v206, v49
	v_cndmask_b32_e64 v49, v49, 0, s[40:41]
	v_readlane_b32 s40, v254, 54
	v_add_f32_e32 v56, v129, v49
	v_readlane_b32 s41, v254, 55
	s_nop 1
	v_cndmask_b32_e64 v49, v49, v56, s[40:41]
	v_sub_f32_e32 v56, v160, v207
	v_min_f32_e32 v56, 0, v56
	v_mul_f32_e32 v56, 0x3fb8aa3b, v56
	v_exp_f32_e32 v56, v56
	v_readlane_b32 s40, v254, 56
	v_readlane_b32 s41, v254, 57
	v_mul_f32_e32 v50, v56, v50
	v_mul_f32_e32 v50, v208, v50
	v_cndmask_b32_e64 v50, v50, 0, s[40:41]
	v_readlane_b32 s40, v254, 58
	v_add_f32_e32 v56, v129, v50
	v_readlane_b32 s41, v254, 59
	s_nop 1
	v_cndmask_b32_e64 v50, v50, v56, s[40:41]
	v_sub_f32_e32 v56, v160, v228
	v_min_f32_e32 v56, 0, v56
	v_mul_f32_e32 v56, 0x3fb8aa3b, v56
	v_exp_f32_e32 v56, v56
	v_readlane_b32 s40, v254, 60
	v_readlane_b32 s41, v254, 61
	v_mul_f32_e32 v51, v56, v51
	v_mul_f32_e32 v51, v229, v51
	v_cndmask_b32_e64 v51, v51, 0, s[40:41]
	v_readlane_b32 s40, v254, 62
	v_add_f32_e32 v56, v129, v51
	v_readlane_b32 s41, v254, 63
	s_nop 1
	v_cndmask_b32_e64 v51, v51, v56, s[40:41]
	v_sub_f32_e32 v56, v160, v230
	v_min_f32_e32 v56, 0, v56
	v_mul_f32_e32 v56, 0x3fb8aa3b, v56
	v_exp_f32_e32 v56, v56
	v_readlane_b32 s40, v255, 0
	v_readlane_b32 s41, v255, 1
	s_waitcnt lgkmcnt(0)
; #define LAS __attribute__((address_space(3)))
; __device__ __forceinline__ float siluf_(float x) { return x * __builtin_amdgcn_rcpf(1.f + __expf(-x)); }
; __device__ __forceinline__ unsigned cvt_pk_bf16(float lo, float hi) { unsigned r; asm volatile("v_cvt_pk_bf16_f32 %0, %1, %2" : "=v"(r) : "v"(lo), "v"(hi)); return r; }
; __device__ void phase_ssd3(const Params& p, bf16_t* ymix, LAS unsigned char* lds, int wg, int nwg) {
;     ...
;             for (int lt = 0; lt < 4; ++lt) {
;                 if (32 * ks > 16 * lt + 15) continue;
;                 const int l = 16 * lt + fr;
;                 const f32x4 c0 = *(LAS const f32x4*)(lds + SSD_CB + (l * 68 + 32 * ks + 8 * fq) * 4), c1 = *(LAS const f32x4*)(lds + SSD_CB + (l * 68 + 32 * ks + 8 * fq + 4) * 4);
;                 float mv[8];
; #pragma unroll
;                 for (int j = 0; j < 8; ++j) { const int s = 32 * ks + 8 * fq + j; const float cbv = j < 4 ? c0[j] : c1[j - 4];
;                     float v = cbv * __expf(fminf(acl[lt] - as_[j], 0.f)) * ds_[j]; v = (s <= l) ? v : 0.f; mv[j] = (s == l) ? v + Dsk : v; }
;                 u32x4 w; w.x = pg8::cvt_pk_bf16(mv[0], mv[1]); w.y = pg8::cvt_pk_bf16(mv[2], mv[3]); w.z = pg8::cvt_pk_bf16(mv[4], mv[5]); w.w = pg8::cvt_pk_bf16(mv[6], mv[7]);
;                 const bf16x8 mf = __builtin_bit_cast(bf16x8, w);
; #pragma unroll
;                 for (int pt = 0; pt < 4; ++pt) acc[pt][lt] = __builtin_amdgcn_mfma_f32_16x16x32_bf16(xa[pt], mf, acc[pt][lt], 0, 0, 0);
;             }
;         }
;         float ssq[4];
; #pragma unroll
;         for (int lt = 0; lt < 4; ++lt) {
;             float s = 0.f;
; #pragma unroll
;             for (int pt = 0; pt < 4; ++pt) {
;                 const f32x4 z = up4(zr[lt][pt]);
;                 f32x4 y = acc[pt][lt];
;                 y.x *= siluf_(z.x); y.y *= siluf_(z.y); y.z *= siluf_(z.z); y.w *= siluf_(z.w);
;                 acc[pt][lt] = y; s += (y.x * y.x + y.y * y.y) + (y.z * y.z + y.w * y.w);
;             }
;             s += __shfl_xor(s, 16); s += __shfl_xor(s, 32); ssq[lt] = s;
	v_mul_f32_e32 v36, v56, v36
	v_mul_f32_e32 v36, v231, v36
	v_cndmask_b32_e64 v36, v36, 0, s[40:41]
	v_readlane_b32 s40, v255, 2
	v_add_f32_e32 v56, v129, v36
	v_readlane_b32 s41, v255, 3
	s_nop 1
	v_cndmask_b32_e64 v56, v36, v56, s[40:41]
	v_sub_f32_e32 v36, v160, v232
	v_min_f32_e32 v36, 0, v36
	v_mul_f32_e32 v36, 0x3fb8aa3b, v36
	v_exp_f32_e32 v36, v36
	v_readlane_b32 s40, v255, 4
	v_readlane_b32 s41, v255, 5
	v_mul_f32_e32 v36, v36, v37
	v_mul_f32_e32 v36, v233, v36
	v_cndmask_b32_e64 v36, v36, 0, s[40:41]
	v_readlane_b32 s40, v255, 6
	v_add_f32_e32 v37, v129, v36
	v_readlane_b32 s41, v255, 7
	s_nop 1
	v_cndmask_b32_e64 v57, v36, v37, s[40:41]
	v_sub_f32_e32 v36, v160, v234
	v_min_f32_e32 v36, 0, v36
	v_mul_f32_e32 v36, 0x3fb8aa3b, v36
	v_exp_f32_e32 v36, v36
	v_readlane_b32 s40, v255, 8
	v_readlane_b32 s41, v255, 9
	v_mul_f32_e32 v36, v36, v38
	v_mul_f32_e32 v36, v235, v36
	v_cndmask_b32_e64 v36, v36, 0, s[40:41]
	v_readlane_b32 s40, v255, 10
	v_add_f32_e32 v37, v129, v36
	v_readlane_b32 s41, v255, 11
	s_nop 1
	v_cndmask_b32_e64 v58, v36, v37, s[40:41]
	v_sub_f32_e32 v36, v160, v236
	v_min_f32_e32 v36, 0, v36
	v_mul_f32_e32 v36, 0x3fb8aa3b, v36
	v_exp_f32_e32 v36, v36
	v_readlane_b32 s40, v255, 12
	v_readlane_b32 s41, v255, 13
	v_mul_f32_e32 v36, v36, v39
	v_mul_f32_e32 v36, v237, v36
	v_cndmask_b32_e64 v36, v36, 0, s[40:41]
	v_add_f32_e32 v37, v129, v36
	v_cndmask_b32_e64 v39, v36, v37, s[96:97]
	v_cvt_pk_bf16_f32 v36, v48, v49
	v_cvt_pk_bf16_f32 v37, v50, v51
	v_cvt_pk_bf16_f32 v38, v56, v57
	v_cvt_pk_bf16_f32 v39, v58, v39
	s_nop 1
	v_mfma_f32_16x16x32_bf16 v[60:63], v[64:67], v[36:39], v[76:79]
	s_nop 2
	v_sub_f32_e32 v76, v161, v131
	v_min_f32_e32 v76, 0, v76
	v_mul_f32_e32 v76, 0x3fb8aa3b, v76
	v_mfma_f32_16x16x32_bf16 v[56:59], v[84:87], v[36:39], v[72:75]
	v_exp_f32_e32 v76, v76
	v_mfma_f32_16x16x32_bf16 v[48:51], v[88:91], v[36:39], v[68:71]
	s_nop 2
	ds_read_b128 v[68:71], v226
	ds_read_b128 v[72:75], v226 offset:16
	s_waitcnt lgkmcnt(1)
	v_mul_f32_e32 v68, v76, v68
	v_mul_f32_e32 v68, v133, v68
	v_cndmask_b32_e64 v68, v68, 0, s[0:1]
	v_add_f32_e32 v76, v129, v68
	v_cndmask_b32_e64 v68, v68, v76, s[72:73]
	v_sub_f32_e32 v76, v161, v195
	v_min_f32_e32 v76, 0, v76
	v_mul_f32_e32 v76, 0x3fb8aa3b, v76
	v_exp_f32_e32 v76, v76
	v_mfma_f32_16x16x32_bf16 v[36:39], v[92:95], v[36:39], v[80:83]
	v_mul_f32_e32 v69, v76, v69
	v_mul_f32_e32 v69, v206, v69
	v_cndmask_b32_e64 v69, v69, 0, s[18:19]
	v_add_f32_e32 v76, v129, v69
	v_cndmask_b32_e64 v69, v69, v76, s[52:53]
	v_sub_f32_e32 v76, v161, v207
	v_min_f32_e32 v76, 0, v76
	v_mul_f32_e32 v76, 0x3fb8aa3b, v76
	v_exp_f32_e32 v76, v76
	v_cvt_pk_bf16_f32 v68, v68, v69
	s_nop 0
	v_mul_f32_e32 v70, v76, v70
	v_mul_f32_e32 v70, v208, v70
	v_cndmask_b32_e64 v70, v70, 0, s[46:47]
	v_add_f32_e32 v76, v129, v70
	v_cndmask_b32_e64 v70, v70, v76, s[50:51]
	v_sub_f32_e32 v76, v161, v228
	v_min_f32_e32 v76, 0, v76
	v_mul_f32_e32 v76, 0x3fb8aa3b, v76
	v_exp_f32_e32 v76, v76
	s_nop 0
	v_mul_f32_e32 v71, v76, v71
	v_mul_f32_e32 v71, v229, v71
	v_cndmask_b32_e64 v71, v71, 0, s[64:65]
	v_add_f32_e32 v76, v129, v71
	v_cndmask_b32_e64 v71, v71, v76, s[20:21]
	v_sub_f32_e32 v76, v161, v230
	v_min_f32_e32 v76, 0, v76
	v_mul_f32_e32 v76, 0x3fb8aa3b, v76
	v_exp_f32_e32 v76, v76
	v_cvt_pk_bf16_f32 v69, v70, v71
	s_waitcnt lgkmcnt(0)
	v_mul_f32_e32 v72, v76, v72
	v_mul_f32_e32 v72, v231, v72
	v_cndmask_b32_e64 v72, v72, 0, s[22:23]
	v_add_f32_e32 v76, v129, v72
	v_cndmask_b32_e64 v72, v72, v76, s[24:25]
	v_sub_f32_e32 v76, v161, v232
	v_min_f32_e32 v76, 0, v76
	v_mul_f32_e32 v76, 0x3fb8aa3b, v76
	v_exp_f32_e32 v76, v76
	s_nop 0
	v_mul_f32_e32 v73, v76, v73
	v_mul_f32_e32 v73, v233, v73
	v_cndmask_b32_e64 v73, v73, 0, s[26:27]
	v_add_f32_e32 v76, v129, v73
	v_cndmask_b32_e64 v73, v73, v76, s[28:29]
	v_sub_f32_e32 v76, v161, v234
	v_min_f32_e32 v76, 0, v76
	v_mul_f32_e32 v76, 0x3fb8aa3b, v76
	v_exp_f32_e32 v76, v76
	v_cvt_pk_bf16_f32 v70, v72, v73
	s_nop 0
	v_mul_f32_e32 v74, v76, v74
	v_mul_f32_e32 v74, v235, v74
	v_cndmask_b32_e64 v74, v74, 0, s[30:31]
	v_add_f32_e32 v76, v129, v74
	v_cndmask_b32_e64 v74, v74, v76, s[34:35]
	v_sub_f32_e32 v76, v161, v236
	v_min_f32_e32 v76, 0, v76
	v_mul_f32_e32 v76, 0x3fb8aa3b, v76
	v_exp_f32_e32 v76, v76
	s_nop 0
	v_mul_f32_e32 v75, v76, v75
	v_mul_f32_e32 v75, v237, v75
	v_cndmask_b32_e64 v75, v75, 0, s[36:37]
	v_add_f32_e32 v76, v129, v75
	v_cndmask_b32_e64 v75, v75, v76, s[38:39]
	v_cvt_pk_bf16_f32 v71, v74, v75
	s_nop 0
	v_mfma_f32_16x16x32_bf16 v[28:31], v[64:67], v[68:71], v[28:31]
	v_xor_b32_e32 v64, 16, v198
	v_add_u32_e32 v65, 64, v227
	v_cmp_lt_i32_e32 vcc, v64, v65
	v_mfma_f32_16x16x32_bf16 v[16:19], v[84:87], v[68:71], v[16:19]
	s_nop 0
	v_cndmask_b32_e32 v64, v198, v64, vcc
	v_lshlrev_b32_e32 v80, 2, v64
	v_xor_b32_e32 v64, 32, v198
	v_cmp_lt_i32_e32 vcc, v64, v65
	s_waitcnt vmcnt(15)
; #define LAS __attribute__((address_space(3)))
; __device__ __forceinline__ float siluf_(float x) { return x * __builtin_amdgcn_rcpf(1.f + __expf(-x)); }
; __device__ void phase_ssd3(const Params& p, bf16_t* ymix, LAS unsigned char* lds, int wg, int nwg) {
;     ...
;         float ssq[4];
; #pragma unroll
;         for (int lt = 0; lt < 4; ++lt) {
;             float s = 0.f;
; #pragma unroll
;             for (int pt = 0; pt < 4; ++pt) {
;                 const f32x4 z = up4(zr[lt][pt]);
;                 f32x4 y = acc[pt][lt];
;                 y.x *= siluf_(z.x); y.y *= siluf_(z.y); y.z *= siluf_(z.z); y.w *= siluf_(z.w);
;                 acc[pt][lt] = y; s += (y.x * y.x + y.y * y.y) + (y.z * y.z + y.w * y.w);
;             }
;             s += __shfl_xor(s, 16); s += __shfl_xor(s, 32); ssq[lt] = s;
;             if (fq == 0) ((LAS float*)(lds + SSD_PART))[e * 64 + 16 * lt + fr] = s;
	v_and_b32_e32 v65, 0xffff0000, v158
	v_mul_f32_e32 v67, 0xbfb8aa3b, v65
	v_cndmask_b32_e32 v64, v198, v64, vcc
	v_lshlrev_b32_e32 v81, 2, v64
	v_lshlrev_b32_e32 v64, 16, v158
	v_mul_f32_e32 v66, 0xbfb8aa3b, v64
	v_exp_f32_e32 v66, v66
	v_exp_f32_e32 v67, v67
	v_mfma_f32_16x16x32_bf16 v[4:7], v[88:91], v[68:71], v[4:7]
	v_add_f32_e32 v66, 1.0, v66
	v_add_f32_e32 v67, 1.0, v67
	v_rcp_f32_e32 v66, v66
	v_rcp_f32_e32 v67, v67
	v_mfma_f32_16x16x32_bf16 v[0:3], v[92:95], v[68:71], v[0:3]
	v_mul_f32_e64 v64, v66, v64
	v_mul_f32_e64 v65, v67, v65
	v_pk_mul_f32 v[52:53], v[64:65], v[52:53]
	v_lshlrev_b32_e32 v64, 16, v159
	v_and_b32_e32 v65, 0xffff0000, v159
	v_mul_f32_e32 v66, 0xbfb8aa3b, v64
	v_mul_f32_e32 v67, 0xbfb8aa3b, v65
	v_exp_f32_e32 v66, v66
	v_exp_f32_e32 v67, v67
	v_pk_mul_f32 v[68:69], v[52:53], v[52:53]
	v_add_f32_e32 v66, 1.0, v66
	v_add_f32_e32 v67, 1.0, v67
	v_rcp_f32_e32 v66, v66
	v_rcp_f32_e32 v67, v67
	v_add_f32_e32 v68, v68, v69
	v_pk_mul_f32 v[64:65], v[66:67], v[64:65]
	s_nop 0
	v_pk_mul_f32 v[54:55], v[64:65], v[54:55]
	s_waitcnt vmcnt(14)
	v_lshlrev_b32_e32 v64, 16, v156
	v_and_b32_e32 v65, 0xffff0000, v156
	v_mul_f32_e32 v66, 0xbfb8aa3b, v64
	v_mul_f32_e32 v67, 0xbfb8aa3b, v65
	v_exp_f32_e32 v66, v66
	v_exp_f32_e32 v67, v67
	v_pk_mul_f32 v[70:71], v[54:55], v[54:55]
	v_add_f32_e32 v66, 1.0, v66
	v_add_f32_e32 v67, 1.0, v67
	v_rcp_f32_e32 v66, v66
	v_rcp_f32_e32 v67, v67
	v_add_f32_e32 v70, v70, v71
	v_add_f32_e32 v68, v68, v70
	v_pk_mul_f32 v[64:65], v[66:67], v[64:65]
	s_nop 0
	v_pk_mul_f32 v[44:45], v[64:65], v[44:45]
	v_lshlrev_b32_e32 v64, 16, v157
	v_and_b32_e32 v65, 0xffff0000, v157
	v_mul_f32_e32 v66, 0xbfb8aa3b, v64
	v_mul_f32_e32 v67, 0xbfb8aa3b, v65
	v_exp_f32_e32 v66, v66
	v_exp_f32_e32 v67, v67
	v_pk_mul_f32 v[72:73], v[44:45], v[44:45]
	v_add_f32_e32 v66, 1.0, v66
	v_add_f32_e32 v67, 1.0, v67
	v_rcp_f32_e32 v66, v66
	v_rcp_f32_e32 v67, v67
	v_add_f32_e32 v72, v72, v73
	v_pk_mul_f32 v[64:65], v[66:67], v[64:65]
	s_nop 0
	v_pk_mul_f32 v[46:47], v[64:65], v[46:47]
	s_waitcnt vmcnt(13)
	v_lshlrev_b32_e32 v64, 16, v154
	v_and_b32_e32 v65, 0xffff0000, v154
	v_mul_f32_e32 v66, 0xbfb8aa3b, v64
	v_mul_f32_e32 v67, 0xbfb8aa3b, v65
	v_exp_f32_e32 v66, v66
	v_exp_f32_e32 v67, v67
	v_pk_mul_f32 v[74:75], v[46:47], v[46:47]
	v_add_f32_e32 v66, 1.0, v66
	v_add_f32_e32 v67, 1.0, v67
	v_rcp_f32_e32 v66, v66
	v_rcp_f32_e32 v67, v67
	v_add_f32_e32 v74, v74, v75
	v_add_f32_e32 v72, v72, v74
	v_add_f32_e32 v68, v68, v72
	v_pk_mul_f32 v[64:65], v[66:67], v[64:65]
	s_nop 0
	v_pk_mul_f32 v[32:33], v[64:65], v[32:33]
	v_lshlrev_b32_e32 v64, 16, v155
	v_and_b32_e32 v65, 0xffff0000, v155
	v_mul_f32_e32 v66, 0xbfb8aa3b, v64
	v_mul_f32_e32 v67, 0xbfb8aa3b, v65
	v_exp_f32_e32 v66, v66
	v_exp_f32_e32 v67, v67
	v_pk_mul_f32 v[76:77], v[32:33], v[32:33]
	v_add_f32_e32 v66, 1.0, v66
	v_add_f32_e32 v67, 1.0, v67
	v_rcp_f32_e32 v66, v66
	v_rcp_f32_e32 v67, v67
	v_add_f32_e32 v70, v76, v77
	v_pk_mul_f32 v[64:65], v[66:67], v[64:65]
	s_nop 0
	v_pk_mul_f32 v[34:35], v[64:65], v[34:35]
	s_waitcnt vmcnt(12)
	v_lshlrev_b32_e32 v64, 16, v152
	v_and_b32_e32 v65, 0xffff0000, v152
	v_mul_f32_e32 v66, 0xbfb8aa3b, v64
	v_mul_f32_e32 v67, 0xbfb8aa3b, v65
	v_exp_f32_e32 v66, v66
	v_exp_f32_e32 v67, v67
	v_pk_mul_f32 v[78:79], v[34:35], v[34:35]
	v_add_f32_e32 v66, 1.0, v66
	v_add_f32_e32 v67, 1.0, v67
	v_rcp_f32_e32 v66, v66
	v_rcp_f32_e32 v67, v67
	v_add_f32_e32 v69, v78, v79
	v_add_f32_e32 v69, v70, v69
	v_add_f32_e32 v68, v68, v69
	v_pk_mul_f32 v[64:65], v[66:67], v[64:65]
	s_nop 0
	v_pk_mul_f32 v[64:65], v[64:65], v[20:21]
	v_lshlrev_b32_e32 v20, 16, v153
	v_and_b32_e32 v21, 0xffff0000, v153
	v_mul_f32_e32 v66, 0xbfb8aa3b, v20
	v_mul_f32_e32 v67, 0xbfb8aa3b, v21
	v_exp_f32_e32 v66, v66
	v_exp_f32_e32 v67, v67
	v_add_f32_e32 v66, 1.0, v66
	v_add_f32_e32 v67, 1.0, v67
	v_rcp_f32_e32 v66, v66
	v_rcp_f32_e32 v67, v67
	s_nop 0
	v_pk_mul_f32 v[20:21], v[66:67], v[20:21]
	s_nop 0
	v_pk_mul_f32 v[66:67], v[20:21], v[22:23]
	v_pk_mul_f32 v[20:21], v[64:65], v[64:65]
	v_pk_mul_f32 v[22:23], v[66:67], v[66:67]
	v_add_f32_e32 v20, v20, v21
	v_add_f32_e32 v22, v22, v23
	v_add_f32_e32 v20, v20, v22
	v_add_f32_e32 v20, v68, v20
	ds_bpermute_b32 v21, v80, v20
	s_waitcnt lgkmcnt(0)
	v_add_f32_e32 v20, v20, v21
	ds_bpermute_b32 v21, v81, v20
	s_and_saveexec_b64 s[40:41], s[2:3]
	s_cbranch_execz .LBB0_874
	s_waitcnt lgkmcnt(0)
	v_add_f32_e32 v20, v20, v21
	ds_write_b32 v125, v20
